# GLA pass-2: step-4 LDS operand reads software-pipelined through a VGPR ring; RB gate loads hoisted ahead of next-chunk prefetch with counted vmcnt
# speedup vs baseline: 1.0063x; 1.0063x over previous
; #define GBAR() asm volatile("s_waitcnt lgkmcnt(0)\n\ts_barrier" ::: "memory")
; template <int MODE> __device__ __forceinline__ void chain(int b, int h, int seg, float* __restrict__ SLOC, float* __restrict__ DTOT, const bf16_t* __restrict__ QB, const bf16_t* __restrict__ KB, const bf16_t* __restrict__ VB, bf16_t* __restrict__ OB, const bf16_t* __restrict__ RB, const float* __res ...
;     ...
;         GBAR();
;         if (MODE == 1) {
; #pragma unroll
;         for (int tb = 0; tb < 2; ++tb) { float tot = 0.f;
; #pragma unroll
;             for (int w = 0; w < 8; ++w) tot += SSQ[w * 64 + 32 * tb + r32];
;             const float rstd = 1.0f / sqrtf(tot * (1.0f / 256.0f) + LN_EPS);
.LBB0_673:
	s_or_b64 exec, exec, s[4:5]
	s_waitcnt lgkmcnt(0)
	s_barrier
	s_waitcnt lgkmcnt(1)
	ds_read2_b32 v[186:187], v173 offset1:32
	ds_read2_b32 v[190:191], v173 offset0:64 offset1:96
	ds_read2_b32 v[192:193], v173 offset0:128 offset1:160
	ds_read2_b32 v[194:195], v173 offset0:192 offset1:224
	v_lshlrev_b32_e32 v206, 16, v132
	s_waitcnt lgkmcnt(3)
	v_add_f32_e32 v185, 0, v186
	v_add_u32_e32 v186, 0x400, v173
	ds_read2_b32 v[196:197], v186 offset1:32
	ds_read2_b32 v[198:199], v186 offset0:64 offset1:96
	s_waitcnt lgkmcnt(4)
	v_add_f32_e32 v185, v185, v190
	ds_read2_b32 v[200:201], v186 offset0:128 offset1:160
	s_waitcnt lgkmcnt(4)
	v_add_f32_e32 v185, v185, v192
	ds_read2_b32 v[202:203], v186 offset0:192 offset1:224
	s_waitcnt lgkmcnt(4)
	v_add_f32_e32 v185, v185, v194
	s_waitcnt lgkmcnt(3)
	v_add_f32_e32 v185, v185, v196
	s_waitcnt lgkmcnt(2)
	v_add_f32_e32 v185, v185, v198
	s_waitcnt lgkmcnt(1)
	v_add_f32_e32 v185, v185, v200
	s_waitcnt lgkmcnt(0)
; __device__ __forceinline__ float bflo(unsigned w) { return __uint_as_float(w << 16); }
; __device__ __forceinline__ float bfhi(unsigned w) { return __uint_as_float(w & 0xffff0000u); }
; __device__ __forceinline__ float bflo(unsigned w) { return __uint_as_float(w << 16); }
; __device__ __forceinline__ float bfhi(unsigned w) { return __uint_as_float(w & 0xffff0000u); }
; __device__ __forceinline__ unsigned pk(float lo, float hi) { typedef float f2 __attribute__((ext_vector_type(2))); typedef __bf16 b2 __attribute__((ext_vector_type(2))); f2 v = {lo, hi}; b2 b = __builtin_convertvector(v, b2); return __builtin_bit_cast(unsigned, b); }
; __device__ __forceinline__ unsigned pk(float lo, float hi) { return gla::pk(lo, hi); }
; template <int MODE> __device__ __forceinline__ void chain(int b, int h, int seg, float* __restrict__ SLOC, float* __restrict__ DTOT, const bf16_t* __restrict__ QB, const bf16_t* __restrict__ KB, const bf16_t* __restrict__ VB, bf16_t* __restrict__ OB, const bf16_t* __restrict__ RB, const float* __res ...
;     ...
;         for (int tb = 0; tb < 2; ++tb) { float tot = 0.f;
; #pragma unroll
;             for (int w = 0; w < 8; ++w) tot += SSQ[w * 64 + 32 * tb + r32];
;             const float rstd = 1.0f / sqrtf(tot * (1.0f / 256.0f) + LN_EPS);
; #pragma unroll
;             for (int g = 0; g < 4; ++g) { const u32x2 rw = rbv[tb][g];
;                 const float y0 = o[tb][4 * g] * rstd * bflo(rw.x), y1 = o[tb][4 * g + 1] * rstd * bfhi(rw.x);
;                 const float y2 = o[tb][4 * g + 2] * rstd * bflo(rw.y), y3 = o[tb][4 * g + 3] * rstd * bfhi(rw.y);
;                 *(u32x2*)((char*)(OB + (row0 + 32 * tb) * 1024 + h * 256 + 32 * wid + 8 * g) + lor) = (u32x2){pk(y0, y1), pk(y2, y3)}; } }
	v_add_f32_e32 v185, v185, v202
	v_fmamk_f32 v185, v185, 0x3b800000, v144
	v_cmp_gt_f32_e32 vcc, s22, v185
	v_mul_f32_e32 v186, 0x4f800000, v185
	v_and_b32_e32 v207, 0xffff0000, v132
	v_cndmask_b32_e32 v185, v185, v186, vcc
	v_sqrt_f32_e32 v186, v185
	v_lshlrev_b32_e32 v132, 16, v133
	v_and_b32_e32 v133, 0xffff0000, v133
	v_lshl_add_u64 v[204:205], v[140:141], 0, s[82:83]
	v_add_u32_e32 v189, -1, v186
	v_fma_f32 v190, -v189, v186, v185
	v_cmp_ge_f32_e64 s[70:71], 0, v190
	v_add_u32_e32 v190, 1, v186
	s_add_u32 s82, s82, 0x20000
	v_cndmask_b32_e64 v189, v186, v189, s[70:71]
	v_fma_f32 v186, -v190, v186, v185
	v_cmp_lt_f32_e64 s[70:71], 0, v186
	s_addc_u32 s83, s83, 0
	s_add_u32 s6, s6, 0x10000
	v_cndmask_b32_e64 v186, v189, v190, s[70:71]
	v_mul_f32_e32 v189, 0x37800000, v186
	v_cndmask_b32_e32 v186, v186, v189, vcc
	v_cmp_class_f32_e32 vcc, v185, v145
	s_addc_u32 s7, s7, 0
	s_add_u32 s74, s74, 0x1000
	v_cndmask_b32_e32 v185, v186, v185, vcc
	v_div_scale_f32 v186, s[4:5], v185, v185, 1.0
	v_rcp_f32_e32 v189, v186
	s_mov_b32 s4, 0x3000000
	s_addc_u32 s75, s75, 0
	s_add_u32 s76, s76, 0x10000
	v_fma_f32 v190, -v186, v189, 1.0
	v_fmac_f32_e32 v189, v190, v189
	v_div_scale_f32 v190, vcc, 1.0, v185, 1.0
	v_mul_f32_e32 v192, v190, v189
	v_fma_f32 v194, -v186, v192, v190
	v_fmac_f32_e32 v192, v194, v189
	v_fma_f32 v186, -v186, v192, v190
	v_div_fmas_f32 v186, v186, v189, v192
	v_div_fixup_f32 v186, v186, v185, 1.0
	v_pk_mul_f32 v[98:99], v[98:99], v[186:187] op_sel_hi:[1,0]
	v_pk_mul_f32 v[100:101], v[100:101], v[186:187] op_sel_hi:[1,0]
	v_pk_mul_f32 v[98:99], v[98:99], v[206:207]
	v_pk_mul_f32 v[100:101], v[100:101], v[132:133]
	v_cvt_pk_bf16_f32 v98, v98, v99
	v_cvt_pk_bf16_f32 v99, v100, v101
	v_add_co_u32_e32 v100, vcc, s4, v204
	s_addc_u32 s77, s77, 0
	s_nop 0
	v_addc_co_u32_e32 v101, vcc, 0, v205, vcc
	global_store_dwordx2 v[100:101], v[98:99], off
	v_pk_mul_f32 v[98:99], v[102:103], v[186:187] op_sel_hi:[1,0]
	v_lshlrev_b32_e32 v102, 16, v130
	v_and_b32_e32 v103, 0xffff0000, v130
	v_pk_mul_f32 v[98:99], v[98:99], v[102:103]
	v_pk_mul_f32 v[102:103], v[104:105], v[186:187] op_sel_hi:[1,0]
	v_lshlrev_b32_e32 v104, 16, v131
	v_and_b32_e32 v105, 0xffff0000, v131
	v_pk_mul_f32 v[102:103], v[102:103], v[104:105]
	v_cvt_pk_bf16_f32 v98, v98, v99
	v_cvt_pk_bf16_f32 v99, v102, v103
	global_store_dwordx2 v[100:101], v[98:99], off offset:16
	v_pk_mul_f32 v[98:99], v[106:107], v[186:187] op_sel_hi:[1,0]
	v_lshlrev_b32_e32 v102, 16, v128
	v_and_b32_e32 v103, 0xffff0000, v128
	v_pk_mul_f32 v[98:99], v[98:99], v[102:103]
	v_pk_mul_f32 v[102:103], v[108:109], v[186:187] op_sel_hi:[1,0]
	v_lshlrev_b32_e32 v104, 16, v129
	v_and_b32_e32 v105, 0xffff0000, v129
	v_pk_mul_f32 v[102:103], v[102:103], v[104:105]
	v_cvt_pk_bf16_f32 v98, v98, v99
	v_cvt_pk_bf16_f32 v99, v102, v103
	global_store_dwordx2 v[100:101], v[98:99], off offset:32
	v_pk_mul_f32 v[98:99], v[110:111], v[186:187] op_sel_hi:[1,0]
	v_lshlrev_b32_e32 v102, 16, v126
	v_and_b32_e32 v103, 0xffff0000, v126
	v_pk_mul_f32 v[98:99], v[98:99], v[102:103]
	v_pk_mul_f32 v[102:103], v[112:113], v[186:187] op_sel_hi:[1,0]
	v_lshlrev_b32_e32 v104, 16, v127
	v_and_b32_e32 v105, 0xffff0000, v127
	v_pk_mul_f32 v[102:103], v[102:103], v[104:105]
	v_cvt_pk_bf16_f32 v98, v98, v99
	v_cvt_pk_bf16_f32 v99, v102, v103
	global_store_dwordx2 v[100:101], v[98:99], off offset:48
	v_add_f32_e32 v98, 0, v187
	v_add_f32_e32 v98, v98, v191
	v_add_f32_e32 v98, v98, v193
	v_add_f32_e32 v98, v98, v195
	v_add_f32_e32 v98, v98, v197
	v_add_f32_e32 v98, v98, v199
	v_add_f32_e32 v98, v98, v201
	v_add_f32_e32 v98, v98, v203
	v_fmamk_f32 v98, v98, 0x3b800000, v144
	v_cmp_gt_f32_e32 vcc, s22, v98
	v_mul_f32_e32 v99, 0x4f800000, v98
	s_cmp_eq_u32 s82, 0x200000
	v_cndmask_b32_e32 v98, v98, v99, vcc
	v_sqrt_f32_e32 v99, v98
	s_nop 0
	v_add_u32_e32 v100, -1, v99
	v_fma_f32 v101, -v100, v99, v98
	v_cmp_ge_f32_e64 s[70:71], 0, v101
	v_add_u32_e32 v101, 1, v99
	s_nop 0
	v_cndmask_b32_e64 v100, v99, v100, s[70:71]
	v_fma_f32 v99, -v101, v99, v98
	v_cmp_lt_f32_e64 s[70:71], 0, v99
	s_nop 1
	v_cndmask_b32_e64 v99, v100, v101, s[70:71]
	v_mul_f32_e32 v100, 0x37800000, v99
	v_cndmask_b32_e32 v99, v99, v100, vcc
	v_cmp_class_f32_e32 vcc, v98, v145
	s_nop 1
	v_cndmask_b32_e32 v98, v99, v98, vcc
	v_div_scale_f32 v99, s[4:5], v98, v98, 1.0
	v_rcp_f32_e32 v100, v99
	s_mov_b32 s4, 0x3010000
	v_fma_f32 v101, -v99, v100, 1.0
	v_fmac_f32_e32 v100, v101, v100
	v_div_scale_f32 v101, vcc, 1.0, v98, 1.0
	v_mul_f32_e32 v102, v101, v100
	v_fma_f32 v103, -v99, v102, v101
	v_fmac_f32_e32 v102, v103, v100
	v_fma_f32 v99, -v99, v102, v101
	v_div_fmas_f32 v99, v99, v100, v102
	v_div_fixup_f32 v98, v99, v98, 1.0
	v_pk_mul_f32 v[82:83], v[82:83], v[98:99] op_sel_hi:[1,0]
	v_lshlrev_b32_e32 v100, 16, v124
	v_and_b32_e32 v101, 0xffff0000, v124
	v_pk_mul_f32 v[82:83], v[82:83], v[100:101]
	v_pk_mul_f32 v[84:85], v[84:85], v[98:99] op_sel_hi:[1,0]
	v_lshlrev_b32_e32 v100, 16, v125
	v_and_b32_e32 v101, 0xffff0000, v125
	v_pk_mul_f32 v[84:85], v[84:85], v[100:101]
	v_cvt_pk_bf16_f32 v82, v82, v83
	v_cvt_pk_bf16_f32 v83, v84, v85
	v_add_co_u32_e32 v84, vcc, s4, v204
	s_nop 1
	v_addc_co_u32_e32 v85, vcc, 0, v205, vcc
	global_store_dwordx2 v[84:85], v[82:83], off
	v_pk_mul_f32 v[82:83], v[86:87], v[98:99] op_sel_hi:[1,0]
	v_lshlrev_b32_e32 v86, 16, v122
	v_and_b32_e32 v87, 0xffff0000, v122
	v_pk_mul_f32 v[82:83], v[82:83], v[86:87]
	v_pk_mul_f32 v[86:87], v[88:89], v[98:99] op_sel_hi:[1,0]
	v_lshlrev_b32_e32 v88, 16, v123
	v_and_b32_e32 v89, 0xffff0000, v123
	v_pk_mul_f32 v[86:87], v[86:87], v[88:89]
	v_cvt_pk_bf16_f32 v82, v82, v83
	v_cvt_pk_bf16_f32 v83, v86, v87
	global_store_dwordx2 v[84:85], v[82:83], off offset:16
	v_pk_mul_f32 v[82:83], v[90:91], v[98:99] op_sel_hi:[1,0]
	v_lshlrev_b32_e32 v86, 16, v120
	v_and_b32_e32 v87, 0xffff0000, v120
	v_pk_mul_f32 v[82:83], v[82:83], v[86:87]
	v_pk_mul_f32 v[86:87], v[92:93], v[98:99] op_sel_hi:[1,0]
	v_lshlrev_b32_e32 v88, 16, v121
	v_and_b32_e32 v89, 0xffff0000, v121
	v_pk_mul_f32 v[86:87], v[86:87], v[88:89]
	v_cvt_pk_bf16_f32 v82, v82, v83
	v_cvt_pk_bf16_f32 v83, v86, v87
	global_store_dwordx2 v[84:85], v[82:83], off offset:32
	v_pk_mul_f32 v[82:83], v[94:95], v[98:99] op_sel_hi:[1,0]
	v_lshlrev_b32_e32 v86, 16, v118
	v_and_b32_e32 v87, 0xffff0000, v118
	v_pk_mul_f32 v[82:83], v[82:83], v[86:87]
	v_pk_mul_f32 v[86:87], v[96:97], v[98:99] op_sel_hi:[1,0]
	v_lshlrev_b32_e32 v88, 16, v119
	v_and_b32_e32 v89, 0xffff0000, v119
	v_pk_mul_f32 v[86:87], v[86:87], v[88:89]
	v_cvt_pk_bf16_f32 v82, v82, v83
	v_cvt_pk_bf16_f32 v83, v86, v87
	global_store_dwordx2 v[84:85], v[82:83], off offset:48
	s_cbranch_scc1 .LBB0_682

; #define GLDS __attribute__((address_space(3)))
; __device__ __forceinline__ unsigned pk(float lo, float hi) { typedef float f2 __attribute__((ext_vector_type(2))); typedef __bf16 b2 __attribute__((ext_vector_type(2))); f2 v = {lo, hi}; b2 b = __builtin_convertvector(v, b2); return __builtin_bit_cast(unsigned, b); }
; #define GBAR() asm volatile("s_waitcnt lgkmcnt(0)\n\ts_barrier" ::: "memory")
; __device__ __forceinline__ unsigned pk(float lo, float hi) { return gla::pk(lo, hi); }
; #define lane lane_id_asm()
; template <int MODE> __device__ __forceinline__ void chain(int b, int h, int seg, float* __restrict__ SLOC, float* __restrict__ DTOT, const bf16_t* __restrict__ QB, const bf16_t* __restrict__ KB, const bf16_t* __restrict__ VB, bf16_t* __restrict__ OB, const bf16_t* __restrict__ RB, const float* __res ...
;     ...
;         GBAR();
;         if (n + 1 < 16) GLA_LOAD(row0 + 64);
;         if (MODE == 1) {
;             const int l15 = lane & 15, kq = lane >> 4, tb16 = wid >> 1, sbA = 2 * (wid & 1);
;             f32x4 a0 = {0.f, 0.f, 0.f, 0.f}, a1 = {0.f, 0.f, 0.f, 0.f};
; #pragma unroll
;             for (int kk = 0; kk < 4; ++kk) {
;                 const bf16x8 qf = *(const GLDS bf16x8*)(L + QT_OFF + (16 * tb16 + l15) * QT_RS + (32 * kk + 8 * kq) * 2);
;                 const bf16x8 kf0 = *(const GLDS bf16x8*)(L + KT_OFF + (16 * sbA + l15) * QT_RS + (32 * kk + 8 * kq) * 2);
;                 const bf16x8 kf1 = *(const GLDS bf16x8*)(L + KT_OFF + (16 * sbA + 16 + l15) * QT_RS + (32 * kk + 8 * kq) * 2);
;                 a0 = __builtin_amdgcn_mfma_f32_16x16x32_bf16(kf0, qf, a0, 0, 0, 0);
;                 a1 = __builtin_amdgcn_mfma_f32_16x16x32_bf16(kf1, qf, a1, 0, 0, 0);
;             }
;             const int t = 16 * tb16 + l15, s0 = 16 * sbA + 4 * kq;
; #pragma unroll
;             for (int i = 0; i < 4; ++i) { if (s0 + i > t) a0[i] = 0.f; if (s0 + 16 + i > t) a1[i] = 0.f; }
;             *(GLDS u32x2*)(L + AM_OFF + t * AM_RS + s0 * 2) = (u32x2){pk(a0[0], a0[1]), pk(a0[2], a0[3])};
;             *(GLDS u32x2*)(L + AM_OFF + t * AM_RS + (s0 + 16) * 2) = (u32x2){pk(a1[0], a1[1]), pk(a1[2], a1[3])};
;     ...
;             for (int g = 0; g < 4; ++g) rbv[tb][g] = *(const u32x2*)((const char*)(RB + (row0 + 32 * tb) * 1024 + h * 256 + 32 * wid + 8 * g) + lor);
.LBB0_676:
	s_waitcnt lgkmcnt(0)
	s_barrier
	v_lshl_add_u64 v[118:119], v[16:17], 0, s[82:83]
	s_mov_b32 s4, 0x27700000
	v_add_co_u32_e32 v120, vcc, s4, v118
	s_mov_b32 s4, 0x27710000
	s_nop 0
	v_addc_co_u32_e32 v121, vcc, 0, v119, vcc
	v_add_co_u32_e32 v118, vcc, s4, v118
	global_load_dwordx2 v[218:219], v[120:121], off
	global_load_dwordx2 v[220:221], v[120:121], off offset:16
	global_load_dwordx2 v[222:223], v[120:121], off offset:32
	global_load_dwordx2 v[224:225], v[120:121], off offset:48
	v_addc_co_u32_e32 v119, vcc, 0, v119, vcc
	global_load_dwordx2 v[226:227], v[118:119], off
	global_load_dwordx2 v[228:229], v[118:119], off offset:16
	global_load_dwordx2 v[230:231], v[118:119], off offset:32
	s_nop 0
	global_load_dwordx2 v[232:233], v[118:119], off offset:48
	s_cmp_eq_u32 s82, 0x1e0000
	s_cbranch_scc1 .LBB0_678
	v_lshl_add_u64 v[4:5], s[76:77], 0, v[2:3]
	v_add_co_u32_e32 v8, vcc, 0x17410000, v4
	v_lshl_add_u64 v[6:7], s[6:7], 0, v[2:3]
	s_nop 0
	v_addc_co_u32_e32 v9, vcc, 0, v5, vcc
	v_add_co_u32_e32 v10, vcc, 0x1b510000, v6
	v_lshl_add_u64 v[12:13], v[142:143], 0, s[82:83]
	s_nop 0
	v_addc_co_u32_e32 v11, vcc, 0, v7, vcc
	v_add_co_u32_e32 v4, vcc, 0x17411000, v4
	global_load_dword v148, v[8:9], off
	global_load_dword v139, v[8:9], off offset:1024
	global_load_dword v149, v[8:9], off offset:2048
	global_load_dword v150, v[8:9], off offset:3072
	global_load_dword v154, v[10:11], off
	global_load_dword v151, v[10:11], off offset:1024
	global_load_dword v152, v[10:11], off offset:2048
	global_load_dword v153, v[10:11], off offset:3072
	v_addc_co_u32_e32 v5, vcc, 0, v5, vcc
	v_add_co_u32_e32 v6, vcc, 0x1b511000, v6
	s_nop 1
	v_addc_co_u32_e32 v7, vcc, 0, v7, vcc
	global_load_dword v155, v[4:5], off
	global_load_dword v156, v[4:5], off offset:1024
	global_load_dword v157, v[4:5], off offset:2048
	global_load_dword v158, v[4:5], off offset:3072
	global_load_dword v159, v[6:7], off
	global_load_dword v160, v[6:7], off offset:1024
	global_load_dword v161, v[6:7], off offset:2048
	global_load_dword v162, v[6:7], off offset:3072
	v_lshl_add_u64 v[4:5], s[74:75], 0, v[2:3]
	v_add_co_u32_e32 v4, vcc, 0x2801000, v4
	s_nop 1
	v_addc_co_u32_e32 v5, vcc, 0, v5, vcc
	global_load_dword v165, v[4:5], off
	global_load_dword v166, v[4:5], off offset:256
	v_add_co_u32_e32 v4, vcc, 0x1f620000, v12
	s_nop 1
	v_addc_co_u32_e32 v5, vcc, 0, v13, vcc
	v_add_co_u32_e32 v8, vcc, 0x1f628000, v12
	s_nop 1
	v_addc_co_u32_e32 v9, vcc, 0, v13, vcc
	v_add_co_u32_e32 v14, vcc, 0x1f630000, v12
	global_load_dwordx4 v[4:7], v[4:5], off
	s_nop 0
	global_load_dwordx4 v[8:11], v[8:9], off
	v_addc_co_u32_e32 v15, vcc, 0, v13, vcc
	v_add_co_u32_e32 v82, vcc, 0x1f638000, v12
	s_nop 1
	v_addc_co_u32_e32 v83, vcc, 0, v13, vcc
	global_load_dwordx4 v[12:15], v[14:15], off
	s_nop 0
	global_load_dwordx4 v[114:117], v[82:83], off
.LBB0_678:
	ds_read_b128 v[82:85], v179
	ds_read_b128 v[86:89], v180 offset:17408
	ds_read_b128 v[90:93], v180 offset:21760
	s_waitcnt lgkmcnt(1)
	v_mfma_f32_16x16x32_bf16 v[86:89], v[86:89], v[82:85], 0
	s_waitcnt lgkmcnt(0)
	v_mfma_f32_16x16x32_bf16 v[82:85], v[90:93], v[82:85], 0
	ds_read_b128 v[90:93], v179 offset:64
	ds_read_b128 v[94:97], v180 offset:17472
	ds_read_b128 v[98:101], v180 offset:21824
	s_waitcnt lgkmcnt(1)
	v_mfma_f32_16x16x32_bf16 v[86:89], v[94:97], v[90:93], v[86:89]
	s_waitcnt lgkmcnt(0)
	v_mfma_f32_16x16x32_bf16 v[82:85], v[98:101], v[90:93], v[82:85]
	ds_read_b128 v[90:93], v179 offset:128
	ds_read_b128 v[94:97], v180 offset:17536
	ds_read_b128 v[98:101], v180 offset:21888
	s_waitcnt lgkmcnt(1)
	v_mfma_f32_16x16x32_bf16 v[86:89], v[94:97], v[90:93], v[86:89]
	s_waitcnt lgkmcnt(0)
	v_mfma_f32_16x16x32_bf16 v[82:85], v[98:101], v[90:93], v[82:85]
	ds_read_b128 v[90:93], v179 offset:192
	ds_read_b128 v[94:97], v180 offset:17600
	ds_read_b128 v[98:101], v180 offset:21952
	s_waitcnt lgkmcnt(1)
	v_mfma_f32_16x16x32_bf16 v[86:89], v[94:97], v[90:93], v[86:89]
	s_waitcnt lgkmcnt(0)
	v_mfma_f32_16x16x32_bf16 v[82:85], v[98:101], v[90:93], v[82:85]
	v_mov_b32_e32 v90, s9
	s_nop 4
	v_cndmask_b32_e64 v91, v86, v90, s[54:55]
	s_nop 0
	v_cndmask_b32_e64 v90, v82, v90, s[56:57]
	v_cndmask_b32_e64 v82, v91, v86, s[58:59]
	v_cndmask_b32_e64 v86, 0, v87, s[58:59]
	v_cndmask_b32_e64 v87, v83, 0, s[60:61]
	v_cndmask_b32_e64 v83, v88, 0, s[62:63]
	v_cndmask_b32_e64 v88, v84, 0, s[64:65]
	v_cndmask_b32_e64 v84, v89, 0, s[66:67]
	v_cndmask_b32_e64 v85, v85, 0, s[68:69]
	v_cvt_pk_bf16_f32 v82, v82, v86
	v_cvt_pk_bf16_f32 v83, v83, v84
	v_cvt_pk_bf16_f32 v84, v90, v87
	v_cvt_pk_bf16_f32 v85, v88, v85
	ds_write2_b64 v181, v[82:83], v[84:85] offset1:4
	s_waitcnt lgkmcnt(0)
	s_barrier
; template <int MODE> __device__ __forceinline__ void chain(int b, int h, int seg, float* __restrict__ SLOC, float* __restrict__ DTOT, const bf16_t* __restrict__ QB, const bf16_t* __restrict__ KB, const bf16_t* __restrict__ VB, bf16_t* __restrict__ OB, const bf16_t* __restrict__ RB, const float* __res ...
;     ...
;         bf16x8 vf[4];
; #pragma unroll
;         for (int ks = 0; ks < 4; ++ks) { const s16x4 lo = trrd(vtr0 + ks * 16 * V_RS), hh = trrd(vtr0 + ks * 16 * V_RS + 4 * V_RS); vf[ks] = (bf16x8){lo[0], lo[1], lo[2], lo[3], hh[0], hh[1], hh[2], hh[3]}; }
;         f32x16 o[2]; o[0] = f32x16{}; o[1] = f32x16{};
;         if (MODE == 1) {
; #pragma unroll
;         for (int tb = 0; tb < 2; ++tb)
; #pragma unroll
;             for (int ks = 0; ks < 4; ++ks) { const bf16x8 af = *(const GLDS bf16x8*)(L + AM_OFF + (32 * tb + r32) * AM_RS + (16 * ks + 8 * hi) * 2);
;                 o[tb] = __builtin_amdgcn_mfma_f32_32x32x16_bf16(vf[ks], af, o[tb], 0, 0, 0); }
;         __builtin_amdgcn_sched_barrier(0);
; #pragma unroll
;         for (int cb = 0; cb < 4; ++cb)
; #pragma unroll
;             for (int j = 0; j < 2; ++j) {
;                 const u32x4 sw = {pk(S[cb][8 * j], S[cb][8 * j + 1]), pk(S[cb][8 * j + 2], S[cb][8 * j + 3]), pk(S[cb][8 * j + 4], S[cb][8 * j + 5]), pk(S[cb][8 * j + 6], S[cb][8 * j + 7])};
;                 const bf16x8 sa = __builtin_bit_cast(bf16x8, sw);
; #pragma unroll
;                 for (int tb = 0; tb < 2; ++tb) { const ldsp qp = L + QT_OFF + (32 * tb + r32) * QT_RS + (32 * cb + 16 * j + 4 * hi) * 2;
;                     const u32x2 x0 = *(const GLDS u32x2*)qp, x1 = *(const GLDS u32x2*)(qp + 16);
;                     const u32x4 qw = {x0.x, x0.y, x1.x, x1.y};
;                     o[tb] = __builtin_amdgcn_mfma_f32_32x32x16_bf16(sa, __builtin_bit_cast(bf16x8, qw), o[tb], 0, 0, 0); }
;                 __builtin_amdgcn_sched_barrier(0);
;             }
;         }
; #pragma unroll
;         for (int cb = 0; cb < 4; ++cb) {
; #pragma unroll
;             for (int g = 0; g < 4; ++g) { const f32x4 e = *(const GLDS f32x4*)(EBL + 32 * cb + 8 * g + 4 * hi);
;                 S[cb][4 * g] *= e[0]; S[cb][4 * g + 1] *= e[1]; S[cb][4 * g + 2] *= e[2]; S[cb][4 * g + 3] *= e[3]; }
; #pragma unroll
;             for (int ks = 0; ks < 4; ++ks) { const bf16x8 kf = *(const GLDS bf16x8*)(L + KH_OFF + (32 * cb + r32) * KH_RS + (16 * ks + 8 * hi) * 2);
	v_add_u32_e32 v185, 0x2000, v183
	v_add_u32_e32 v186, 0x100, v138
	v_add_u32_e32 v186, 0x19400, v186
	ds_read_b64_tr_b16 v[130:131], v163 offset:53248
	ds_read_b64_tr_b16 v[132:133], v163 offset:55552
	ds_read_b128 v[190:193], v182
	ds_read_b128 v[194:197], v182 offset:4608
	ds_read_b64_tr_b16 v[126:127], v163 offset:62464
	ds_read_b64_tr_b16 v[128:129], v163 offset:64768
	ds_read_b128 v[198:201], v182 offset:32
	ds_read_b128 v[202:205], v182 offset:4640
	ds_read_b64_tr_b16 v[122:123], v164 offset:18432
	ds_read_b64_tr_b16 v[124:125], v164 offset:20736
	ds_read_b128 v[206:209], v182 offset:64
	ds_read_b128 v[210:213], v182 offset:4672
	s_waitcnt lgkmcnt(9)
	v_mfma_f32_32x32x16_bf16 v[98:113], v[130:133], v[190:193], 0
	ds_read_b64_tr_b16 v[118:119], v164 offset:27648
	ds_read_b64_tr_b16 v[120:121], v164 offset:29952
	ds_read_b128 v[214:217], v182 offset:96
	s_waitcnt lgkmcnt(11)
	v_mfma_f32_32x32x16_bf16 v[82:97], v[130:133], v[194:197], 0
	ds_read_b128 v[190:193], v182 offset:4704
	s_waitcnt lgkmcnt(9)
	v_mfma_f32_32x32x16_bf16 v[98:113], v[126:129], v[198:201], v[98:113]
	ds_read2_b64 v[194:197], v183 offset0:0 offset1:2
	ds_read2_b64 v[198:201], v185 offset0:64 offset1:66
	s_waitcnt lgkmcnt(10)
	v_mfma_f32_32x32x16_bf16 v[82:97], v[126:129], v[202:205], v[82:97]
	ds_read2_b64 v[202:205], v183 offset0:4 offset1:6
	s_waitcnt lgkmcnt(8)
	v_mfma_f32_32x32x16_bf16 v[98:113], v[122:125], v[206:209], v[98:113]
	ds_read2_b64 v[206:209], v185 offset0:68 offset1:70
	s_waitcnt lgkmcnt(8)
	v_mfma_f32_32x32x16_bf16 v[82:97], v[122:125], v[210:213], v[82:97]
	ds_read2_b64 v[210:213], v183 offset0:8 offset1:10
	s_waitcnt lgkmcnt(6)
	v_mfma_f32_32x32x16_bf16 v[98:113], v[118:121], v[214:217], v[98:113]
	ds_read2_b64 v[214:217], v185 offset0:72 offset1:74
	s_waitcnt lgkmcnt(6)
	v_mfma_f32_32x32x16_bf16 v[82:97], v[118:121], v[190:193], v[82:97]
	ds_read2_b64 v[190:193], v183 offset0:12 offset1:14
	v_cvt_pk_bf16_f32 v234, v66, v67
	v_cvt_pk_bf16_f32 v235, v68, v69
	v_cvt_pk_bf16_f32 v236, v70, v71
	v_cvt_pk_bf16_f32 v237, v72, v73
	s_waitcnt lgkmcnt(6)
	s_nop 1
	v_mfma_f32_32x32x16_bf16 v[98:113], v[234:237], v[194:197], v[98:113]
	v_cvt_pk_bf16_f32 v238, v74, v75
	v_cvt_pk_bf16_f32 v239, v76, v77
	v_cvt_pk_bf16_f32 v240, v78, v79
	v_cvt_pk_bf16_f32 v241, v80, v81
	s_waitcnt lgkmcnt(5)
	v_mfma_f32_32x32x16_bf16 v[82:97], v[234:237], v[198:201], v[82:97]
	ds_read2_b64 v[194:197], v185 offset0:76 offset1:78
	ds_read2_b64 v[198:201], v183 offset0:16 offset1:18
	s_nop 0
	s_waitcnt lgkmcnt(6)
	v_mfma_f32_32x32x16_bf16 v[98:113], v[238:241], v[202:205], v[98:113]
	v_cvt_pk_bf16_f32 v234, v50, v51
	v_cvt_pk_bf16_f32 v235, v52, v53
	v_cvt_pk_bf16_f32 v236, v54, v55
	v_cvt_pk_bf16_f32 v237, v56, v57
	s_waitcnt lgkmcnt(5)
	v_mfma_f32_32x32x16_bf16 v[82:97], v[238:241], v[206:209], v[82:97]
	ds_read2_b64 v[202:205], v185 offset0:80 offset1:82
	ds_read2_b64 v[206:209], v183 offset0:20 offset1:22
	s_nop 0
	s_waitcnt lgkmcnt(6)
	v_mfma_f32_32x32x16_bf16 v[98:113], v[234:237], v[210:213], v[98:113]
	v_cvt_pk_bf16_f32 v238, v58, v59
	v_cvt_pk_bf16_f32 v239, v60, v61
	v_cvt_pk_bf16_f32 v240, v62, v63
	v_cvt_pk_bf16_f32 v241, v64, v65
	s_waitcnt lgkmcnt(5)
	v_mfma_f32_32x32x16_bf16 v[82:97], v[234:237], v[214:217], v[82:97]
	ds_read2_b64 v[210:213], v185 offset0:84 offset1:86
	ds_read2_b64 v[214:217], v183 offset0:24 offset1:26
	s_nop 0
	s_waitcnt lgkmcnt(6)
	v_mfma_f32_32x32x16_bf16 v[98:113], v[238:241], v[190:193], v[98:113]
	v_cvt_pk_bf16_f32 v234, v34, v35
	v_cvt_pk_bf16_f32 v235, v36, v37
	v_cvt_pk_bf16_f32 v236, v38, v39
	v_cvt_pk_bf16_f32 v237, v40, v41
	s_waitcnt lgkmcnt(5)
	v_mfma_f32_32x32x16_bf16 v[82:97], v[238:241], v[194:197], v[82:97]
	ds_read2_b64 v[190:193], v185 offset0:88 offset1:90
	ds_read2_b64 v[194:197], v183 offset0:28 offset1:30
	s_nop 0
	s_waitcnt lgkmcnt(6)
	v_mfma_f32_32x32x16_bf16 v[98:113], v[234:237], v[198:201], v[98:113]
	v_cvt_pk_bf16_f32 v238, v42, v43
	v_cvt_pk_bf16_f32 v239, v44, v45
	v_cvt_pk_bf16_f32 v240, v46, v47
	v_cvt_pk_bf16_f32 v241, v48, v49
	s_waitcnt lgkmcnt(5)
	v_mfma_f32_32x32x16_bf16 v[82:97], v[234:237], v[202:205], v[82:97]
	ds_read2_b64 v[198:201], v185 offset0:92 offset1:94
	ds_read_b128 v[202:205], v186
	s_nop 0
	s_waitcnt lgkmcnt(6)
	v_mfma_f32_32x32x16_bf16 v[98:113], v[238:241], v[206:209], v[98:113]
	v_cvt_pk_bf16_f32 v234, v18, v19
	v_cvt_pk_bf16_f32 v235, v20, v21
	v_cvt_pk_bf16_f32 v236, v22, v23
	v_cvt_pk_bf16_f32 v237, v24, v25
	s_waitcnt lgkmcnt(5)
	v_mfma_f32_32x32x16_bf16 v[82:97], v[238:241], v[210:213], v[82:97]
	ds_read_b128 v[206:209], v186 offset:32
	ds_read_b128 v[210:213], v186 offset:64
	s_nop 0
	s_waitcnt lgkmcnt(6)
	v_mfma_f32_32x32x16_bf16 v[98:113], v[234:237], v[214:217], v[98:113]
	v_cvt_pk_bf16_f32 v238, v26, v27
	v_cvt_pk_bf16_f32 v239, v28, v29
	v_cvt_pk_bf16_f32 v240, v30, v31
	v_cvt_pk_bf16_f32 v241, v32, v33
	s_waitcnt lgkmcnt(5)
; #define GLDS __attribute__((address_space(3)))
; template <int MODE> __device__ __forceinline__ void chain(int b, int h, int seg, float* __restrict__ SLOC, float* __restrict__ DTOT, const bf16_t* __restrict__ QB, const bf16_t* __restrict__ KB, const bf16_t* __restrict__ VB, bf16_t* __restrict__ OB, const bf16_t* __restrict__ RB, const float* __res ...
;     ...
; #pragma unroll
;         for (int cb = 0; cb < 4; ++cb) {
; #pragma unroll
;             for (int g = 0; g < 4; ++g) { const f32x4 e = *(const GLDS f32x4*)(EBL + 32 * cb + 8 * g + 4 * hi);
;                 S[cb][4 * g] *= e[0]; S[cb][4 * g + 1] *= e[1]; S[cb][4 * g + 2] *= e[2]; S[cb][4 * g + 3] *= e[3]; }
; #pragma unroll
;             for (int ks = 0; ks < 4; ++ks) { const bf16x8 kf = *(const GLDS bf16x8*)(L + KH_OFF + (32 * cb + r32) * KH_RS + (16 * ks + 8 * hi) * 2);
;                 S[cb] = __builtin_amdgcn_mfma_f32_32x32x16_bf16(kf, vf[ks], S[cb], 0, 0, 0); }
;             __builtin_amdgcn_sched_barrier(0);
;         }
	v_mfma_f32_32x32x16_bf16 v[82:97], v[234:237], v[190:193], v[82:97]
	ds_read_b128 v[214:217], v186 offset:96
	ds_read_b128 v[190:193], v184 offset:34816
	s_nop 0
	s_waitcnt lgkmcnt(6)
	v_mfma_f32_32x32x16_bf16 v[98:113], v[238:241], v[194:197], v[98:113]
	s_waitcnt lgkmcnt(5)
	v_mfma_f32_32x32x16_bf16 v[82:97], v[238:241], v[198:201], v[82:97]
	ds_read_b128 v[194:197], v184 offset:34848
	ds_read_b128 v[198:201], v184 offset:34880
	s_waitcnt lgkmcnt(6)
	v_pk_mul_f32 v[66:67], v[66:67], v[202:203]
	v_pk_mul_f32 v[68:69], v[68:69], v[204:205]
	ds_read_b128 v[202:205], v184 offset:34912
	s_waitcnt lgkmcnt(6)
	v_pk_mul_f32 v[70:71], v[70:71], v[206:207]
	v_pk_mul_f32 v[72:73], v[72:73], v[208:209]
	ds_read_b128 v[206:209], v186 offset:128
	s_waitcnt lgkmcnt(6)
	v_pk_mul_f32 v[74:75], v[74:75], v[210:211]
	v_pk_mul_f32 v[76:77], v[76:77], v[212:213]
	ds_read_b128 v[210:213], v186 offset:160
	s_waitcnt lgkmcnt(6)
	v_pk_mul_f32 v[78:79], v[78:79], v[214:215]
	v_pk_mul_f32 v[80:81], v[80:81], v[216:217]
	ds_read_b128 v[214:217], v186 offset:192
	s_waitcnt lgkmcnt(6)
	s_nop 1
	v_mfma_f32_32x32x16_bf16 v[66:81], v[190:193], v[130:133], v[66:81]
	ds_read_b128 v[190:193], v186 offset:224
	s_waitcnt lgkmcnt(6)
	v_mfma_f32_32x32x16_bf16 v[66:81], v[194:197], v[126:129], v[66:81]
	ds_read_b128 v[194:197], v184 offset:39424
	s_waitcnt lgkmcnt(6)
	v_mfma_f32_32x32x16_bf16 v[66:81], v[198:201], v[122:125], v[66:81]
	ds_read_b128 v[198:201], v184 offset:39456
	s_waitcnt lgkmcnt(6)
	v_mfma_f32_32x32x16_bf16 v[66:81], v[202:205], v[118:121], v[66:81]
	ds_read_b128 v[202:205], v184 offset:39488
	s_waitcnt lgkmcnt(6)
	v_pk_mul_f32 v[50:51], v[50:51], v[206:207]
	v_pk_mul_f32 v[52:53], v[52:53], v[208:209]
	ds_read_b128 v[206:209], v184 offset:39520
	s_waitcnt lgkmcnt(6)
	v_pk_mul_f32 v[54:55], v[54:55], v[210:211]
	v_pk_mul_f32 v[56:57], v[56:57], v[212:213]
	ds_read_b128 v[210:213], v186 offset:256
	s_waitcnt lgkmcnt(6)
	v_pk_mul_f32 v[58:59], v[58:59], v[214:215]
	v_pk_mul_f32 v[60:61], v[60:61], v[216:217]
	ds_read_b128 v[214:217], v186 offset:288
	s_waitcnt lgkmcnt(6)
	v_pk_mul_f32 v[62:63], v[62:63], v[190:191]
	v_pk_mul_f32 v[64:65], v[64:65], v[192:193]
	ds_read_b128 v[190:193], v186 offset:320
	s_waitcnt lgkmcnt(6)
	s_nop 1
	v_mfma_f32_32x32x16_bf16 v[50:65], v[194:197], v[130:133], v[50:65]
	ds_read_b128 v[194:197], v186 offset:352
	s_waitcnt lgkmcnt(6)
	v_mfma_f32_32x32x16_bf16 v[50:65], v[198:201], v[126:129], v[50:65]
	ds_read_b128 v[198:201], v184 offset:44032
	s_waitcnt lgkmcnt(6)
	v_mfma_f32_32x32x16_bf16 v[50:65], v[202:205], v[122:125], v[50:65]
	ds_read_b128 v[202:205], v184 offset:44064
	s_waitcnt lgkmcnt(6)
	v_mfma_f32_32x32x16_bf16 v[50:65], v[206:209], v[118:121], v[50:65]
	ds_read_b128 v[206:209], v184 offset:44096
	s_waitcnt lgkmcnt(6)
	v_pk_mul_f32 v[34:35], v[34:35], v[210:211]
	v_pk_mul_f32 v[36:37], v[36:37], v[212:213]
	ds_read_b128 v[210:213], v184 offset:44128
	s_waitcnt lgkmcnt(6)
	v_pk_mul_f32 v[38:39], v[38:39], v[214:215]
	v_pk_mul_f32 v[40:41], v[40:41], v[216:217]
	ds_read_b128 v[214:217], v186 offset:384
	s_waitcnt lgkmcnt(6)
	v_pk_mul_f32 v[42:43], v[42:43], v[190:191]
	v_pk_mul_f32 v[44:45], v[44:45], v[192:193]
	ds_read_b128 v[190:193], v186 offset:416
	s_waitcnt lgkmcnt(6)
	v_pk_mul_f32 v[46:47], v[46:47], v[194:195]
	v_pk_mul_f32 v[48:49], v[48:49], v[196:197]
	ds_read_b128 v[194:197], v186 offset:448
	s_waitcnt lgkmcnt(6)
	s_nop 1
	v_mfma_f32_32x32x16_bf16 v[34:49], v[198:201], v[130:133], v[34:49]
	ds_read_b128 v[198:201], v186 offset:480
	s_waitcnt lgkmcnt(6)
	v_mfma_f32_32x32x16_bf16 v[34:49], v[202:205], v[126:129], v[34:49]
	ds_read_b128 v[202:205], v184 offset:48640
	s_waitcnt lgkmcnt(6)
	v_mfma_f32_32x32x16_bf16 v[34:49], v[206:209], v[122:125], v[34:49]
	ds_read_b128 v[206:209], v184 offset:48672
	s_waitcnt lgkmcnt(6)
	v_mfma_f32_32x32x16_bf16 v[34:49], v[210:213], v[118:121], v[34:49]
	ds_read_b128 v[210:213], v184 offset:48704
	s_waitcnt lgkmcnt(6)
	v_pk_mul_f32 v[18:19], v[18:19], v[214:215]
	v_pk_mul_f32 v[20:21], v[20:21], v[216:217]
	ds_read_b128 v[214:217], v184 offset:48736
	s_waitcnt lgkmcnt(6)
	v_pk_mul_f32 v[22:23], v[22:23], v[190:191]
	v_pk_mul_f32 v[24:25], v[24:25], v[192:193]
	s_waitcnt lgkmcnt(5)
	v_pk_mul_f32 v[26:27], v[26:27], v[194:195]
	v_pk_mul_f32 v[28:29], v[28:29], v[196:197]
	s_waitcnt lgkmcnt(4)
	v_pk_mul_f32 v[30:31], v[30:31], v[198:199]
	v_pk_mul_f32 v[32:33], v[32:33], v[200:201]
	s_waitcnt lgkmcnt(3)
	s_nop 1
	v_mfma_f32_32x32x16_bf16 v[18:33], v[202:205], v[130:133], v[18:33]
	s_waitcnt lgkmcnt(2)
	v_mfma_f32_32x32x16_bf16 v[18:33], v[206:209], v[126:129], v[18:33]
	s_waitcnt lgkmcnt(1)
	v_mfma_f32_32x32x16_bf16 v[18:33], v[210:213], v[122:125], v[18:33]
	s_waitcnt lgkmcnt(0)
	v_mfma_f32_32x32x16_bf16 v[18:33], v[214:217], v[118:121], v[18:33]
	s_cmp_eq_u32 s82, 0x1e0000
	s_cbranch_scc1 .Lgla_rbv_last
	s_waitcnt vmcnt(22)
	s_branch .Lgla_rbv_ok

; template <int MODE> __device__ __forceinline__ void chain(int b, int h, int seg, float* __restrict__ SLOC, float* __restrict__ DTOT, const bf16_t* __restrict__ QB, const bf16_t* __restrict__ KB, const bf16_t* __restrict__ VB, bf16_t* __restrict__ OB, const bf16_t* __restrict__ RB, const float* __res ...
;     ...
;         u32x2 rbv[2][4];
;         if (MODE == 1) {
; #pragma unroll
;         for (int tb = 0; tb < 2; ++tb)
; #pragma unroll
;             for (int g = 0; g < 4; ++g) rbv[tb][g] = *(const u32x2*)((const char*)(RB + (row0 + 32 * tb) * 1024 + h * 256 + 32 * wid + 8 * g) + lor);
; #pragma unroll
;         for (int tb = 0; tb < 2; ++tb) { float ss = 0.f;
; #pragma unroll
;             for (int r = 0; r < 16; ++r) ss += o[tb][r] * o[tb][r];
;             ss += __shfl_xor(ss, 32);
;             if (hi == 0) SSQ[wid * 64 + 32 * tb + r32] = ss; }
.Lgla_rbv_ok:
	v_mov_b32_e32 v132, v218
	v_mov_b32_e32 v133, v219
	v_mov_b32_e32 v130, v220
	v_mov_b32_e32 v131, v221
	v_mov_b32_e32 v128, v222
	v_mov_b32_e32 v129, v223
	v_mov_b32_e32 v126, v224
	v_mov_b32_e32 v127, v225
	v_mov_b32_e32 v124, v226
	v_mov_b32_e32 v125, v227
	v_mov_b32_e32 v122, v228
	v_mov_b32_e32 v123, v229
	v_mov_b32_e32 v120, v230
	v_mov_b32_e32 v121, v231
	v_mov_b32_e32 v118, v232
	v_mov_b32_e32 v119, v233
	v_and_b32_e32 v186, 64, v1
	v_xor_b32_e32 v185, 32, v1
	v_add_u32_e32 v186, 64, v186
	v_cmp_lt_i32_e32 vcc, v185, v186
	v_mul_f32_e32 v186, v99, v99
	v_fmac_f32_e32 v186, v98, v98
	v_fmac_f32_e32 v186, v100, v100
	v_fmac_f32_e32 v186, v101, v101
	v_fmac_f32_e32 v186, v102, v102
	v_fmac_f32_e32 v186, v103, v103
	v_fmac_f32_e32 v186, v104, v104
	v_fmac_f32_e32 v186, v105, v105
	v_fmac_f32_e32 v186, v106, v106
	v_fmac_f32_e32 v186, v107, v107
	v_fmac_f32_e32 v186, v108, v108
	v_fmac_f32_e32 v186, v109, v109
	v_fmac_f32_e32 v186, v110, v110
	v_fmac_f32_e32 v186, v111, v111
	v_cndmask_b32_e32 v185, v1, v185, vcc
	v_fmac_f32_e32 v186, v112, v112
	v_lshlrev_b32_e32 v185, 2, v185
	v_fmac_f32_e32 v186, v113, v113
	ds_bpermute_b32 v187, v185, v186
	s_and_saveexec_b64 s[4:5], s[52:53]
	s_cbranch_execz .LBB0_680
	s_waitcnt lgkmcnt(0)
	v_add_f32_e32 v186, v186, v187
	ds_write_b32 v172, v186

; #define PG8_STAGE(bufoff, gbase, voff) do { _Pragma("unroll") for (int _i = 0; _i < 2; ++_i) \
;         __builtin_amdgcn_global_load_lds((const unsigned*)((const char*)(gbase) + (voff)[_i]), (PG8_LAS unsigned*)(lds + (bufoff) + ldsw + _i * 8192), 16, 0, 0); } while (0)
; #define PG8_WAIT_V(n) asm volatile("s_waitcnt vmcnt(" #n ")" ::: "memory")
; #define PG8_BAR __builtin_amdgcn_s_barrier()
; template <class Epi, class Sched, bool ALIGN_EPI = false, bool SP2 = false>
; __device__ __forceinline__ void gemm_phase(PG8_LAS unsigned char* lds, const Gemm g, const Sched& S, const Epi& E, const int wv) {
;     ...
;         PG8_STAGE(PG8_SB(0, 0), cB, voffB); PG8_STAGE(PG8_SB(0, 1), cB + hstep, voffB); PG8_STAGE(PG8_SA(0, 0), cA, voffA); PG8_STAGE(PG8_SA(0, 1), cA + hstep, voffA);
;         if (wr == 1) PG8_BAR;
;         PG8_WAIT_V(2); PG8_BAR;
;         PG8_STAGE(PG8_SB(1, 0), cB + kstep, voffB); PG8_STAGE(PG8_SA(1, 0), cA + kstep, voffA); PG8_STAGE(PG8_SB(1, 1), cB + hstep + kstep, voffB);
;         PG8_WAIT_V(6); PG8_BAR;
;     } else {
;         PG8_STAGE(PG8_SB(0, 0), cB, voffB); PG8_STAGE(PG8_SA(0, 0), cA, voffA); PG8_STAGE(PG8_SB(0, 1), cB + hstep, voffB); PG8_STAGE(PG8_SA(0, 1), cA + hstep, voffA);
;         if (wr == 1) PG8_BAR;
;         PG8_WAIT_V(4); PG8_BAR;
;         PG8_STAGE(PG8_SB(1, 0), cB + kstep, voffB); PG8_STAGE(PG8_SA(1, 0), cA + kstep, voffA); PG8_STAGE(PG8_SB(1, 1), cB + hstep + kstep, voffB);
.LBB0_956:
	s_mov_b64 s[14:15], 0x80
	v_lshl_add_u64 v[0:1], v[0:1], 0, s[14:15]
	s_add_i32 m0, s22, 0x18000
	s_waitcnt vmcnt(2)
	s_barrier
	global_load_lds_dwordx4 v[0:1], off
	v_lshl_add_u64 v[0:1], v[2:3], 0, s[14:15]
	s_add_i32 m0, s22, 0x1a000
	s_add_i32 s39, s22, 0x8000
	s_add_i32 s52, s22, 0xa000
	global_load_lds_dwordx4 v[0:1], off
	v_lshl_add_u64 v[0:1], v[4:5], 0, s[14:15]
	s_mov_b32 m0, s39
	s_add_u32 s12, s72, 0x40080
	global_load_lds_dwordx4 v[0:1], off
	v_lshl_add_u64 v[0:1], v[6:7], 0, s[14:15]
	s_mov_b32 m0, s52
	s_addc_u32 s13, s73, 0
	global_load_lds_dwordx4 v[0:1], off
	v_lshl_add_u64 v[0:1], s[12:13], 0, v[130:131]
	s_add_i32 m0, s22, 0x1c000
	v_and_b32_e32 v15, 15, v14
	global_load_lds_dwordx4 v[0:1], off
	v_lshl_add_u64 v[0:1], s[12:13], 0, v[134:135]
	s_add_i32 m0, s22, 0x1e000
	v_lshrrev_b32_e32 v16, 1, v14
	global_load_lds_dwordx4 v[0:1], off
	v_lshlrev_b32_e32 v0, 14, v8
	v_and_b32_e32 v0, 0xffff8000, v0
	v_or_b32_e32 v166, s95, v15
	v_and_b32_e32 v16, 24, v16
	v_lshl_add_u32 v0, v9, 11, v0
	v_and_b32_e32 v1, 1, v8
	v_lshlrev_b32_e32 v17, 6, v166
	v_lshlrev_b32_e32 v18, 1, v16
	s_movk_i32 s5, 0x3c0
	v_lshlrev_b32_e32 v19, 2, v166
	v_lshl_or_b32 v0, v1, 6, v0
	v_and_or_b32 v17, v17, s5, v18
	v_and_b32_e32 v19, 32, v19
	v_readlane_b32 s5, v246, 16
	v_lshlrev_b32_e32 v14, 2, v14
	v_lshl_add_u32 v136, v10, 1, v0
	v_lshlrev_b32_e32 v0, 14, v11
	v_bitop3_b32 v17, v17, s5, v19 bitop3:0xde
	v_lshl_or_b32 v15, v15, 6, v18
	v_and_b32_e32 v14, 32, v14
	v_readlane_b32 s5, v245, 54
	v_readlane_b32 s12, v245, 53
	v_and_b32_e32 v0, 0xffff8000, v0
	v_bitop3_b32 v14, v15, s5, v14 bitop3:0xde
	s_mov_b32 s5, 0x18000
	s_mov_b32 s26, 0x1c000
	s_waitcnt vmcnt(6)
	v_or_b32_e32 v167, s12, v16
	v_lshl_add_u32 v0, v12, 11, v0
	v_and_b32_e32 v1, 1, v11
	s_mov_b32 s12, 0x14000
	v_lshl_or_b32 v0, v1, 6, v0
	s_add_i32 s54, s23, 0x100
	s_add_i32 s55, s12, 0x100
	s_brev_b32 s50, 15
	s_mov_b32 s60, 0xf0000200
	s_add_i32 s76, s5, 0x100
	s_add_i32 s77, s26, 0x100
	v_mov_b32_e32 v137, v131
	v_lshl_add_u32 v138, v13, 1, v0
	v_mov_b32_e32 v139, v131
	s_mov_b32 s53, 0
	v_mov_b64_e32 v[140:141], 0x400
	v_mov_b64_e32 v[142:143], 0x3ff
	v_add_u32_e32 v168, s54, v14
	v_add_u32_e32 v169, s55, v14
	v_add_u32_e32 v170, 0x100, v17
	s_mov_b32 s57, 0x10080
	s_mov_b32 s51, -1
	s_mov_b32 s56, 0x3f9837f0
	s_mov_b64 s[58:59], 0x200
	s_mov_b32 s61, -1
	v_add_u32_e32 v171, s76, v14
	v_add_u32_e32 v172, s77, v14
	s_barrier
	s_branch .LBB0_959

; __device__ __forceinline__ u32x4 pack8(f32x4 a, f32x4 b) { u32x4 w; w.x = cvt_pk_bf16(a[0], a[1]); w.y = cvt_pk_bf16(a[2], a[3]); w.z = cvt_pk_bf16(b[0], b[1]); w.w = cvt_pk_bf16(b[2], b[3]); return w; }
; #define EPI_LOOP(...) \
;     _Pragma("unroll") for (int ai = 0; ai < 2; ++ai) _Pragma("unroll") for (int m = 0; m < 4; ++m) { const int row = u.pm * BM + ai * HALF + wr * 64 + m * 16 + fr; \
;         _Pragma("unroll") for (int bj = 0; bj < 2; ++bj) { const int cl = bj * HALF + wc * 32 + 8 * fq; f32x4 v0 = acc[ai][bj][m][0], v1 = acc[ai][bj][m][1]; __VA_ARGS__ } }
;     __device__ __forceinline__ void core(int row, int gc, f32x4 v0, f32x4 v1) const { *(u32x4*)(T + (size_t)row * 1024 + gc) = pack8(v0, v1); }
;     __device__ __forceinline__ void core(int row, int gc, f32x4 v0, f32x4 v1) const {
;         const size_t off = (size_t)row * 1024 + gc; f32x4 x0 = {0.f, 0.f, 0.f, 0.f}, x1 = {0.f, 0.f, 0.f, 0.f};
;         if (row < MROWS) { const float* b = row < MP ? xp + off : xs + (off - (size_t)MP * 1024); x0 = *(const f32x4*)b; x1 = *(const f32x4*)(b + 4); }
;         *(u32x4*)(Z + off) = pack8(x0 * ALPHA + v0, x1 * ALPHA + v1);
;     }
;     __device__ __forceinline__ void operator()(const f32x4 (&acc)[2][2][4][2], const Unit& u, int wr, int wc, int fr, int fq) const {
;         EPI_LOOP({ core(row, u.pn * BM + cl, v0, v1); })
.LBB0_969:
	v_lshl_add_u32 v146, s44, 8, v166
	v_lshl_or_b32 v144, s4, 8, v167
	v_ashrrev_i32_e32 v147, 31, v146
	v_lshlrev_b64 v[148:149], 10, v[146:147]
	v_ashrrev_i32_e32 v145, 31, v144
	v_lshl_add_u64 v[156:157], v[148:149], 0, v[144:145]
	v_lshlrev_b64 v[154:155], 2, v[156:157]
	v_cmp_gt_i32_e64 s[44:45], s57, v146
	v_cmp_gt_i32_e32 vcc, s23, v146
	v_mov_b32_e32 v150, 0
	v_lshl_add_u64 v[152:153], s[8:9], 0, v[154:155]
	v_lshl_add_u64 v[154:155], s[46:47], 0, v[154:155]
	v_mov_b32_e32 v158, 0
	v_mov_b32_e32 v159, 0
	v_mov_b32_e32 v160, 0
	v_mov_b32_e32 v161, 0
	v_mov_b32_e32 v162, 0
	v_mov_b32_e32 v163, 0
	v_mov_b32_e32 v164, 0
	v_mov_b32_e32 v165, 0
	s_and_saveexec_b64 s[4:5], s[44:45]
	s_cbranch_execz .LBB0_971
	v_lshl_add_u64 v[158:159], v[154:155], 0, s[50:51]
	v_cndmask_b32_e32 v163, v159, v153, vcc
	v_cndmask_b32_e32 v162, v158, v152, vcc
	global_load_dwordx4 v[158:161], v[162:163], off
	global_load_dwordx4 v[174:177], v[162:163], off offset:16
	s_waitcnt vmcnt(0)
	v_pk_mul_f32 v[164:165], v[160:161], s[56:57] op_sel_hi:[1,0]
	v_pk_mul_f32 v[162:163], v[158:159], s[56:57] op_sel_hi:[1,0]
	v_pk_mul_f32 v[160:161], v[176:177], s[56:57] op_sel_hi:[1,0]
	v_pk_mul_f32 v[158:159], v[174:175], s[56:57] op_sel_hi:[1,0]
.LBB0_971:
	s_or_b64 exec, exec, s[4:5]
	v_pk_add_f32 v[124:125], v[124:125], v[162:163]
	v_pk_add_f32 v[160:161], v[122:123], v[160:161]
	v_pk_add_f32 v[122:123], v[120:121], v[158:159]
	v_pk_add_f32 v[126:127], v[126:127], v[164:165]
	v_cvt_pk_bf16_f32 v120, v124, v125
	v_lshl_add_u64 v[124:125], v[156:157], 1, s[48:49]
	v_cvt_pk_bf16_f32 v121, v126, v127
	v_cvt_pk_bf16_f32 v122, v122, v123
	v_cvt_pk_bf16_f32 v123, v160, v161
	global_store_dwordx4 v[124:125], v[120:123], off
	v_mov_b32_e32 v151, 0
	v_mov_b32_e32 v124, 0
	v_mov_b32_e32 v122, 0
	v_mov_b32_e32 v123, 0
	v_mov_b32_e32 v125, 0
	v_mov_b32_e32 v126, 0
	v_mov_b32_e32 v127, 0
	s_and_saveexec_b64 s[4:5], s[44:45]
	s_cbranch_execz .LBB0_973
	v_lshl_add_u64 v[120:121], v[152:153], 0, s[58:59]
	v_lshl_add_u64 v[122:123], v[154:155], 0, s[60:61]
	v_cndmask_b32_e32 v125, v123, v121, vcc
	v_cndmask_b32_e32 v124, v122, v120, vcc
	global_load_dwordx4 v[120:123], v[124:125], off
	global_load_dwordx4 v[150:153], v[124:125], off offset:16
	s_waitcnt vmcnt(0)
	v_pk_mul_f32 v[126:127], v[122:123], s[56:57] op_sel_hi:[1,0]
	v_pk_mul_f32 v[124:125], v[120:121], s[56:57] op_sel_hi:[1,0]
	v_pk_mul_f32 v[122:123], v[152:153], s[56:57] op_sel_hi:[1,0]
	v_pk_mul_f32 v[150:151], v[150:151], s[56:57] op_sel_hi:[1,0]
.LBB0_973:
	s_or_b64 exec, exec, s[4:5]
	v_or_b32_e32 v120, 0x80, v144
	v_ashrrev_i32_e32 v121, 31, v120
	v_lshl_add_u64 v[148:149], v[148:149], 0, v[120:121]
	v_pk_add_f32 v[116:117], v[116:117], v[124:125]
	v_pk_add_f32 v[122:123], v[114:115], v[122:123]
	v_pk_add_f32 v[114:115], v[112:113], v[150:151]
	v_pk_add_f32 v[118:119], v[118:119], v[126:127]
	v_cvt_pk_bf16_f32 v112, v116, v117
	v_lshl_add_u64 v[116:117], v[148:149], 1, s[48:49]
	v_cvt_pk_bf16_f32 v113, v118, v119
	v_cvt_pk_bf16_f32 v114, v114, v115
	v_cvt_pk_bf16_f32 v115, v122, v123
	global_store_dwordx4 v[116:117], v[112:115], off
	v_mov_b32_e32 v124, 0
	v_mov_b32_e32 v125, 0
	v_or_b32_e32 v114, 16, v146
	v_ashrrev_i32_e32 v115, 31, v114
	v_lshlrev_b64 v[112:113], 10, v[114:115]
	v_lshl_add_u64 v[122:123], v[112:113], 0, v[144:145]
	v_lshlrev_b64 v[118:119], 2, v[122:123]
	v_cmp_gt_i32_e64 s[44:45], s57, v114
	v_cmp_gt_i32_e32 vcc, s23, v114
	v_mov_b32_e32 v114, 0
	v_lshl_add_u64 v[116:117], s[8:9], 0, v[118:119]
	v_lshl_add_u64 v[118:119], s[46:47], 0, v[118:119]
	v_mov_b32_e32 v126, 0
	v_mov_b32_e32 v127, 0
	v_mov_b32_e32 v148, 0
	v_mov_b32_e32 v149, 0
	v_mov_b32_e32 v150, 0
	v_mov_b32_e32 v151, 0
	s_and_saveexec_b64 s[4:5], s[44:45]
	v_readlane_b32 s74, v246, 27
	v_readlane_b32 s75, v246, 28
	s_cbranch_execz .LBB0_975
	v_lshl_add_u64 v[124:125], v[118:119], 0, s[50:51]
	v_cndmask_b32_e32 v149, v125, v117, vcc
	v_cndmask_b32_e32 v148, v124, v116, vcc
	global_load_dwordx4 v[124:127], v[148:149], off
	global_load_dwordx4 v[152:155], v[148:149], off offset:16
	s_waitcnt vmcnt(0)
	v_pk_mul_f32 v[150:151], v[126:127], s[56:57] op_sel_hi:[1,0]
	v_pk_mul_f32 v[148:149], v[124:125], s[56:57] op_sel_hi:[1,0]
	v_pk_mul_f32 v[126:127], v[154:155], s[56:57] op_sel_hi:[1,0]
	v_pk_mul_f32 v[124:125], v[152:153], s[56:57] op_sel_hi:[1,0]
.LBB0_975:
	s_or_b64 exec, exec, s[4:5]
	v_pk_add_f32 v[108:109], v[108:109], v[148:149]
	v_pk_add_f32 v[126:127], v[106:107], v[126:127]
	v_pk_add_f32 v[106:107], v[104:105], v[124:125]
	v_pk_add_f32 v[110:111], v[110:111], v[150:151]
	v_cvt_pk_bf16_f32 v104, v108, v109
	v_lshl_add_u64 v[108:109], v[122:123], 1, s[48:49]
	v_cvt_pk_bf16_f32 v105, v110, v111
	v_cvt_pk_bf16_f32 v106, v106, v107
	v_cvt_pk_bf16_f32 v107, v126, v127
	global_store_dwordx4 v[108:109], v[104:107], off
	v_mov_b32_e32 v115, 0
	v_mov_b32_e32 v108, 0
	v_mov_b32_e32 v104, 0
	v_mov_b32_e32 v105, 0
	v_mov_b32_e32 v106, 0
	v_mov_b32_e32 v107, 0
	v_mov_b32_e32 v109, 0
	s_and_saveexec_b64 s[4:5], s[44:45]
	s_cbranch_execz .LBB0_977
	v_lshl_add_u64 v[104:105], v[116:117], 0, s[58:59]
	v_lshl_add_u64 v[106:107], v[118:119], 0, s[60:61]
	v_cndmask_b32_e32 v109, v107, v105, vcc
	v_cndmask_b32_e32 v108, v106, v104, vcc
	global_load_dwordx4 v[104:107], v[108:109], off
	global_load_dwordx4 v[114:117], v[108:109], off offset:16
	s_waitcnt vmcnt(0)
	v_pk_mul_f32 v[108:109], v[106:107], s[56:57] op_sel_hi:[1,0]
	v_pk_mul_f32 v[106:107], v[104:105], s[56:57] op_sel_hi:[1,0]
	v_pk_mul_f32 v[104:105], v[116:117], s[56:57] op_sel_hi:[1,0]
	v_pk_mul_f32 v[114:115], v[114:115], s[56:57] op_sel_hi:[1,0]
; __device__ __forceinline__ u32x4 pack8(f32x4 a, f32x4 b) { u32x4 w; w.x = cvt_pk_bf16(a[0], a[1]); w.y = cvt_pk_bf16(a[2], a[3]); w.z = cvt_pk_bf16(b[0], b[1]); w.w = cvt_pk_bf16(b[2], b[3]); return w; }
; #define EPI_LOOP(...) \
;     _Pragma("unroll") for (int ai = 0; ai < 2; ++ai) _Pragma("unroll") for (int m = 0; m < 4; ++m) { const int row = u.pm * BM + ai * HALF + wr * 64 + m * 16 + fr; \
;         _Pragma("unroll") for (int bj = 0; bj < 2; ++bj) { const int cl = bj * HALF + wc * 32 + 8 * fq; f32x4 v0 = acc[ai][bj][m][0], v1 = acc[ai][bj][m][1]; __VA_ARGS__ } }
;     __device__ __forceinline__ void core(int row, int gc, f32x4 v0, f32x4 v1) const { *(u32x4*)(T + (size_t)row * 1024 + gc) = pack8(v0, v1); }
;     __device__ __forceinline__ void core(int row, int gc, f32x4 v0, f32x4 v1) const {
;         const size_t off = (size_t)row * 1024 + gc; f32x4 x0 = {0.f, 0.f, 0.f, 0.f}, x1 = {0.f, 0.f, 0.f, 0.f};
;         if (row < MROWS) { const float* b = row < MP ? xp + off : xs + (off - (size_t)MP * 1024); x0 = *(const f32x4*)b; x1 = *(const f32x4*)(b + 4); }
;         *(u32x4*)(Z + off) = pack8(x0 * ALPHA + v0, x1 * ALPHA + v1);
;     }
;     __device__ __forceinline__ void operator()(const f32x4 (&acc)[2][2][4][2], const Unit& u, int wr, int wc, int fr, int fq) const {
;         EPI_LOOP({ core(row, u.pn * BM + cl, v0, v1); })
.LBB0_977:
	s_or_b64 exec, exec, s[4:5]
	v_lshl_add_u64 v[110:111], v[112:113], 0, v[120:121]
	v_pk_add_f32 v[100:101], v[100:101], v[106:107]
	v_pk_add_f32 v[104:105], v[98:99], v[104:105]
	v_pk_add_f32 v[98:99], v[96:97], v[114:115]
	v_pk_add_f32 v[102:103], v[102:103], v[108:109]
	v_cvt_pk_bf16_f32 v96, v100, v101
	v_lshl_add_u64 v[100:101], v[110:111], 1, s[48:49]
	v_cvt_pk_bf16_f32 v97, v102, v103
	v_cvt_pk_bf16_f32 v98, v98, v99
	v_cvt_pk_bf16_f32 v99, v104, v105
	global_store_dwordx4 v[100:101], v[96:99], off
	v_mov_b32_e32 v106, 0
	v_mov_b32_e32 v107, 0
	v_or_b32_e32 v98, 32, v146
	v_ashrrev_i32_e32 v99, 31, v98
	v_lshlrev_b64 v[96:97], 10, v[98:99]
	v_lshl_add_u64 v[104:105], v[96:97], 0, v[144:145]
	v_lshlrev_b64 v[102:103], 2, v[104:105]
	v_cmp_gt_i32_e64 s[44:45], s57, v98
	v_cmp_gt_i32_e32 vcc, s23, v98
	v_mov_b32_e32 v98, 0
	v_lshl_add_u64 v[100:101], s[8:9], 0, v[102:103]
	v_lshl_add_u64 v[102:103], s[46:47], 0, v[102:103]
	v_mov_b32_e32 v108, 0
	v_mov_b32_e32 v109, 0
	v_mov_b32_e32 v110, 0
	v_mov_b32_e32 v111, 0
	v_mov_b32_e32 v112, 0
	v_mov_b32_e32 v113, 0
	s_and_saveexec_b64 s[4:5], s[44:45]
	s_cbranch_execz .LBB0_979
	v_lshl_add_u64 v[106:107], v[102:103], 0, s[50:51]
	v_cndmask_b32_e32 v111, v107, v101, vcc
	v_cndmask_b32_e32 v110, v106, v100, vcc
	global_load_dwordx4 v[106:109], v[110:111], off
	global_load_dwordx4 v[114:117], v[110:111], off offset:16
	s_waitcnt vmcnt(0)
	v_pk_mul_f32 v[112:113], v[108:109], s[56:57] op_sel_hi:[1,0]
	v_pk_mul_f32 v[110:111], v[106:107], s[56:57] op_sel_hi:[1,0]
	v_pk_mul_f32 v[108:109], v[116:117], s[56:57] op_sel_hi:[1,0]
	v_pk_mul_f32 v[106:107], v[114:115], s[56:57] op_sel_hi:[1,0]
.LBB0_979:
	s_or_b64 exec, exec, s[4:5]
	v_pk_add_f32 v[92:93], v[92:93], v[110:111]
	v_pk_add_f32 v[108:109], v[90:91], v[108:109]
	v_pk_add_f32 v[90:91], v[88:89], v[106:107]
	v_pk_add_f32 v[94:95], v[94:95], v[112:113]
	v_cvt_pk_bf16_f32 v88, v92, v93
	v_lshl_add_u64 v[92:93], v[104:105], 1, s[48:49]
	v_cvt_pk_bf16_f32 v89, v94, v95
	v_cvt_pk_bf16_f32 v90, v90, v91
	v_cvt_pk_bf16_f32 v91, v108, v109
	global_store_dwordx4 v[92:93], v[88:91], off
	v_mov_b32_e32 v99, 0
	v_mov_b32_e32 v92, 0
	v_mov_b32_e32 v88, 0
	v_mov_b32_e32 v89, 0
	v_mov_b32_e32 v90, 0
	v_mov_b32_e32 v91, 0
	v_mov_b32_e32 v93, 0
	s_and_saveexec_b64 s[4:5], s[44:45]
	s_cbranch_execz .LBB0_981
	v_lshl_add_u64 v[88:89], v[100:101], 0, s[58:59]
	v_lshl_add_u64 v[90:91], v[102:103], 0, s[60:61]
	v_cndmask_b32_e32 v93, v91, v89, vcc
	v_cndmask_b32_e32 v92, v90, v88, vcc
	global_load_dwordx4 v[88:91], v[92:93], off
	global_load_dwordx4 v[98:101], v[92:93], off offset:16
	s_waitcnt vmcnt(0)
	v_pk_mul_f32 v[92:93], v[90:91], s[56:57] op_sel_hi:[1,0]
	v_pk_mul_f32 v[90:91], v[88:89], s[56:57] op_sel_hi:[1,0]
	v_pk_mul_f32 v[88:89], v[100:101], s[56:57] op_sel_hi:[1,0]
	v_pk_mul_f32 v[98:99], v[98:99], s[56:57] op_sel_hi:[1,0]
.LBB0_981:
	s_or_b64 exec, exec, s[4:5]
	v_lshl_add_u64 v[94:95], v[96:97], 0, v[120:121]
	v_pk_add_f32 v[84:85], v[84:85], v[90:91]
	v_pk_add_f32 v[88:89], v[82:83], v[88:89]
	v_pk_add_f32 v[82:83], v[80:81], v[98:99]
	v_pk_add_f32 v[86:87], v[86:87], v[92:93]
	v_cvt_pk_bf16_f32 v80, v84, v85
	v_lshl_add_u64 v[84:85], v[94:95], 1, s[48:49]
	v_cvt_pk_bf16_f32 v81, v86, v87
	v_cvt_pk_bf16_f32 v82, v82, v83
	v_cvt_pk_bf16_f32 v83, v88, v89
	global_store_dwordx4 v[84:85], v[80:83], off
	v_mov_b32_e32 v90, 0
	v_mov_b32_e32 v91, 0
	v_or_b32_e32 v82, 48, v146
	v_ashrrev_i32_e32 v83, 31, v82
	v_lshlrev_b64 v[80:81], 10, v[82:83]
	v_lshl_add_u64 v[88:89], v[80:81], 0, v[144:145]
	v_lshlrev_b64 v[86:87], 2, v[88:89]
	v_cmp_gt_i32_e64 s[44:45], s57, v82
	v_cmp_gt_i32_e32 vcc, s23, v82
	v_mov_b32_e32 v82, 0
	v_lshl_add_u64 v[84:85], s[8:9], 0, v[86:87]
	v_lshl_add_u64 v[86:87], s[46:47], 0, v[86:87]
	v_mov_b32_e32 v92, 0
	v_mov_b32_e32 v93, 0
	v_mov_b32_e32 v94, 0
	v_mov_b32_e32 v95, 0
	v_mov_b32_e32 v96, 0
	v_mov_b32_e32 v97, 0
	s_and_saveexec_b64 s[4:5], s[44:45]
	s_cbranch_execz .LBB0_983
	v_lshl_add_u64 v[90:91], v[86:87], 0, s[50:51]
	v_cndmask_b32_e32 v95, v91, v85, vcc
	v_cndmask_b32_e32 v94, v90, v84, vcc
	global_load_dwordx4 v[90:93], v[94:95], off
	global_load_dwordx4 v[98:101], v[94:95], off offset:16
	s_waitcnt vmcnt(0)
	v_pk_mul_f32 v[96:97], v[92:93], s[56:57] op_sel_hi:[1,0]
	v_pk_mul_f32 v[94:95], v[90:91], s[56:57] op_sel_hi:[1,0]
	v_pk_mul_f32 v[92:93], v[100:101], s[56:57] op_sel_hi:[1,0]
	v_pk_mul_f32 v[90:91], v[98:99], s[56:57] op_sel_hi:[1,0]
.LBB0_983:
	s_or_b64 exec, exec, s[4:5]
	v_pk_add_f32 v[76:77], v[76:77], v[94:95]
	v_pk_add_f32 v[92:93], v[74:75], v[92:93]
	v_pk_add_f32 v[74:75], v[72:73], v[90:91]
	v_pk_add_f32 v[78:79], v[78:79], v[96:97]
	v_cvt_pk_bf16_f32 v72, v76, v77
	v_lshl_add_u64 v[76:77], v[88:89], 1, s[48:49]
	v_cvt_pk_bf16_f32 v73, v78, v79
	v_cvt_pk_bf16_f32 v74, v74, v75
	v_cvt_pk_bf16_f32 v75, v92, v93
	global_store_dwordx4 v[76:77], v[72:75], off
	v_mov_b32_e32 v83, 0
	v_mov_b32_e32 v76, 0
	v_mov_b32_e32 v72, 0
	v_mov_b32_e32 v73, 0
	v_mov_b32_e32 v74, 0
	v_mov_b32_e32 v75, 0
	v_mov_b32_e32 v77, 0
	s_and_saveexec_b64 s[4:5], s[44:45]
	s_cbranch_execz .LBB0_985
	v_lshl_add_u64 v[72:73], v[84:85], 0, s[58:59]
	v_lshl_add_u64 v[74:75], v[86:87], 0, s[60:61]
	v_cndmask_b32_e32 v77, v75, v73, vcc
	v_cndmask_b32_e32 v76, v74, v72, vcc
	global_load_dwordx4 v[72:75], v[76:77], off
	global_load_dwordx4 v[82:85], v[76:77], off offset:16
	s_waitcnt vmcnt(0)
	v_pk_mul_f32 v[76:77], v[74:75], s[56:57] op_sel_hi:[1,0]
	v_pk_mul_f32 v[74:75], v[72:73], s[56:57] op_sel_hi:[1,0]
	v_pk_mul_f32 v[72:73], v[84:85], s[56:57] op_sel_hi:[1,0]
	v_pk_mul_f32 v[82:83], v[82:83], s[56:57] op_sel_hi:[1,0]
; __device__ __forceinline__ u32x4 pack8(f32x4 a, f32x4 b) { u32x4 w; w.x = cvt_pk_bf16(a[0], a[1]); w.y = cvt_pk_bf16(a[2], a[3]); w.z = cvt_pk_bf16(b[0], b[1]); w.w = cvt_pk_bf16(b[2], b[3]); return w; }
; #define EPI_LOOP(...) \
;     _Pragma("unroll") for (int ai = 0; ai < 2; ++ai) _Pragma("unroll") for (int m = 0; m < 4; ++m) { const int row = u.pm * BM + ai * HALF + wr * 64 + m * 16 + fr; \
;         _Pragma("unroll") for (int bj = 0; bj < 2; ++bj) { const int cl = bj * HALF + wc * 32 + 8 * fq; f32x4 v0 = acc[ai][bj][m][0], v1 = acc[ai][bj][m][1]; __VA_ARGS__ } }
;     __device__ __forceinline__ void core(int row, int gc, f32x4 v0, f32x4 v1) const { *(u32x4*)(T + (size_t)row * 1024 + gc) = pack8(v0, v1); }
;     __device__ __forceinline__ void core(int row, int gc, f32x4 v0, f32x4 v1) const {
;         const size_t off = (size_t)row * 1024 + gc; f32x4 x0 = {0.f, 0.f, 0.f, 0.f}, x1 = {0.f, 0.f, 0.f, 0.f};
;         if (row < MROWS) { const float* b = row < MP ? xp + off : xs + (off - (size_t)MP * 1024); x0 = *(const f32x4*)b; x1 = *(const f32x4*)(b + 4); }
;         *(u32x4*)(Z + off) = pack8(x0 * ALPHA + v0, x1 * ALPHA + v1);
;     }
;     __device__ __forceinline__ void operator()(const f32x4 (&acc)[2][2][4][2], const Unit& u, int wr, int wc, int fr, int fq) const {
;         EPI_LOOP({ core(row, u.pn * BM + cl, v0, v1); })
.LBB0_985:
	s_or_b64 exec, exec, s[4:5]
	v_lshl_add_u64 v[78:79], v[80:81], 0, v[120:121]
	v_pk_add_f32 v[68:69], v[68:69], v[74:75]
	v_pk_add_f32 v[72:73], v[66:67], v[72:73]
	v_pk_add_f32 v[66:67], v[64:65], v[82:83]
	v_pk_add_f32 v[70:71], v[70:71], v[76:77]
	v_cvt_pk_bf16_f32 v64, v68, v69
	v_lshl_add_u64 v[68:69], v[78:79], 1, s[48:49]
	v_cvt_pk_bf16_f32 v65, v70, v71
	v_cvt_pk_bf16_f32 v66, v66, v67
	v_cvt_pk_bf16_f32 v67, v72, v73
	global_store_dwordx4 v[68:69], v[64:67], off
	v_mov_b32_e32 v74, 0
	v_mov_b32_e32 v75, 0
	v_add_u32_e32 v66, 0x80, v146
	v_ashrrev_i32_e32 v67, 31, v66
	v_lshlrev_b64 v[64:65], 10, v[66:67]
	v_lshl_add_u64 v[72:73], v[64:65], 0, v[144:145]
	v_lshlrev_b64 v[70:71], 2, v[72:73]
	v_cmp_gt_i32_e64 s[44:45], s57, v66
	v_cmp_gt_i32_e32 vcc, s23, v66
	v_mov_b32_e32 v66, 0
	v_lshl_add_u64 v[68:69], s[8:9], 0, v[70:71]
	v_lshl_add_u64 v[70:71], s[46:47], 0, v[70:71]
	v_mov_b32_e32 v76, 0
	v_mov_b32_e32 v77, 0
	v_mov_b32_e32 v78, 0
	v_mov_b32_e32 v79, 0
	v_mov_b32_e32 v80, 0
	v_mov_b32_e32 v81, 0
	s_and_saveexec_b64 s[4:5], s[44:45]
	s_cbranch_execz .LBB0_987
	v_lshl_add_u64 v[74:75], v[70:71], 0, s[50:51]
	v_cndmask_b32_e32 v79, v75, v69, vcc
	v_cndmask_b32_e32 v78, v74, v68, vcc
	global_load_dwordx4 v[74:77], v[78:79], off
	global_load_dwordx4 v[82:85], v[78:79], off offset:16
	s_waitcnt vmcnt(0)
	v_pk_mul_f32 v[80:81], v[76:77], s[56:57] op_sel_hi:[1,0]
	v_pk_mul_f32 v[78:79], v[74:75], s[56:57] op_sel_hi:[1,0]
	v_pk_mul_f32 v[76:77], v[84:85], s[56:57] op_sel_hi:[1,0]
	v_pk_mul_f32 v[74:75], v[82:83], s[56:57] op_sel_hi:[1,0]
.LBB0_987:
	s_or_b64 exec, exec, s[4:5]
	v_pk_add_f32 v[60:61], v[60:61], v[78:79]
	v_pk_add_f32 v[76:77], v[58:59], v[76:77]
	v_pk_add_f32 v[58:59], v[56:57], v[74:75]
	v_pk_add_f32 v[62:63], v[62:63], v[80:81]
	v_cvt_pk_bf16_f32 v56, v60, v61
	v_lshl_add_u64 v[60:61], v[72:73], 1, s[48:49]
	v_cvt_pk_bf16_f32 v57, v62, v63
	v_cvt_pk_bf16_f32 v58, v58, v59
	v_cvt_pk_bf16_f32 v59, v76, v77
	global_store_dwordx4 v[60:61], v[56:59], off
	v_mov_b32_e32 v67, 0
	v_mov_b32_e32 v60, 0
	v_mov_b32_e32 v56, 0
	v_mov_b32_e32 v57, 0
	v_mov_b32_e32 v58, 0
	v_mov_b32_e32 v59, 0
	v_mov_b32_e32 v61, 0
	s_and_saveexec_b64 s[4:5], s[44:45]
	s_cbranch_execz .LBB0_989
	v_lshl_add_u64 v[56:57], v[68:69], 0, s[58:59]
	v_lshl_add_u64 v[58:59], v[70:71], 0, s[60:61]
	v_cndmask_b32_e32 v61, v59, v57, vcc
	v_cndmask_b32_e32 v60, v58, v56, vcc
	global_load_dwordx4 v[56:59], v[60:61], off
	global_load_dwordx4 v[66:69], v[60:61], off offset:16
	s_waitcnt vmcnt(0)
	v_pk_mul_f32 v[60:61], v[58:59], s[56:57] op_sel_hi:[1,0]
	v_pk_mul_f32 v[58:59], v[56:57], s[56:57] op_sel_hi:[1,0]
	v_pk_mul_f32 v[56:57], v[68:69], s[56:57] op_sel_hi:[1,0]
	v_pk_mul_f32 v[66:67], v[66:67], s[56:57] op_sel_hi:[1,0]
.LBB0_989:
	s_or_b64 exec, exec, s[4:5]
	v_lshl_add_u64 v[62:63], v[64:65], 0, v[120:121]
	v_pk_add_f32 v[52:53], v[52:53], v[58:59]
	v_pk_add_f32 v[56:57], v[50:51], v[56:57]
	v_pk_add_f32 v[50:51], v[48:49], v[66:67]
	v_pk_add_f32 v[54:55], v[54:55], v[60:61]
	v_cvt_pk_bf16_f32 v48, v52, v53
	v_lshl_add_u64 v[52:53], v[62:63], 1, s[48:49]
	v_cvt_pk_bf16_f32 v49, v54, v55
	v_cvt_pk_bf16_f32 v50, v50, v51
	v_cvt_pk_bf16_f32 v51, v56, v57
	global_store_dwordx4 v[52:53], v[48:51], off
	v_mov_b32_e32 v58, 0
	v_mov_b32_e32 v59, 0
	v_add_u32_e32 v50, 0x90, v146
	v_ashrrev_i32_e32 v51, 31, v50
	v_lshlrev_b64 v[48:49], 10, v[50:51]
	v_lshl_add_u64 v[56:57], v[48:49], 0, v[144:145]
	v_lshlrev_b64 v[54:55], 2, v[56:57]
	v_cmp_gt_i32_e64 s[44:45], s57, v50
	v_cmp_gt_i32_e32 vcc, s23, v50
	v_mov_b32_e32 v50, 0
	v_lshl_add_u64 v[52:53], s[8:9], 0, v[54:55]
	v_lshl_add_u64 v[54:55], s[46:47], 0, v[54:55]
	v_mov_b32_e32 v60, 0
	v_mov_b32_e32 v61, 0
	v_mov_b32_e32 v62, 0
	v_mov_b32_e32 v63, 0
	v_mov_b32_e32 v64, 0
	v_mov_b32_e32 v65, 0
	s_and_saveexec_b64 s[4:5], s[44:45]
	s_cbranch_execz .LBB0_991
	v_lshl_add_u64 v[58:59], v[54:55], 0, s[50:51]
	v_cndmask_b32_e32 v63, v59, v53, vcc
	v_cndmask_b32_e32 v62, v58, v52, vcc
	global_load_dwordx4 v[58:61], v[62:63], off
	global_load_dwordx4 v[66:69], v[62:63], off offset:16
	s_waitcnt vmcnt(0)
	v_pk_mul_f32 v[64:65], v[60:61], s[56:57] op_sel_hi:[1,0]
	v_pk_mul_f32 v[62:63], v[58:59], s[56:57] op_sel_hi:[1,0]
	v_pk_mul_f32 v[60:61], v[68:69], s[56:57] op_sel_hi:[1,0]
	v_pk_mul_f32 v[58:59], v[66:67], s[56:57] op_sel_hi:[1,0]
.LBB0_991:
	s_or_b64 exec, exec, s[4:5]
	v_pk_add_f32 v[44:45], v[44:45], v[62:63]
	v_pk_add_f32 v[60:61], v[42:43], v[60:61]
	v_pk_add_f32 v[42:43], v[40:41], v[58:59]
	v_pk_add_f32 v[46:47], v[46:47], v[64:65]
	v_cvt_pk_bf16_f32 v40, v44, v45
	v_lshl_add_u64 v[44:45], v[56:57], 1, s[48:49]
	v_cvt_pk_bf16_f32 v41, v46, v47
	v_cvt_pk_bf16_f32 v42, v42, v43
	v_cvt_pk_bf16_f32 v43, v60, v61
	global_store_dwordx4 v[44:45], v[40:43], off
	v_mov_b32_e32 v51, 0
	v_mov_b32_e32 v44, 0
	v_mov_b32_e32 v40, 0
	v_mov_b32_e32 v41, 0
	v_mov_b32_e32 v42, 0
	v_mov_b32_e32 v43, 0
	v_mov_b32_e32 v45, 0
	s_and_saveexec_b64 s[4:5], s[44:45]
	s_cbranch_execz .LBB0_993
	v_lshl_add_u64 v[40:41], v[52:53], 0, s[58:59]
	v_lshl_add_u64 v[42:43], v[54:55], 0, s[60:61]
	v_cndmask_b32_e32 v45, v43, v41, vcc
	v_cndmask_b32_e32 v44, v42, v40, vcc
	global_load_dwordx4 v[40:43], v[44:45], off
	global_load_dwordx4 v[50:53], v[44:45], off offset:16
	s_waitcnt vmcnt(0)
	v_pk_mul_f32 v[44:45], v[42:43], s[56:57] op_sel_hi:[1,0]
	v_pk_mul_f32 v[42:43], v[40:41], s[56:57] op_sel_hi:[1,0]
	v_pk_mul_f32 v[40:41], v[52:53], s[56:57] op_sel_hi:[1,0]
	v_pk_mul_f32 v[50:51], v[50:51], s[56:57] op_sel_hi:[1,0]
; __device__ __forceinline__ u32x4 pack8(f32x4 a, f32x4 b) { u32x4 w; w.x = cvt_pk_bf16(a[0], a[1]); w.y = cvt_pk_bf16(a[2], a[3]); w.z = cvt_pk_bf16(b[0], b[1]); w.w = cvt_pk_bf16(b[2], b[3]); return w; }
; #define EPI_LOOP(...) \
;     _Pragma("unroll") for (int ai = 0; ai < 2; ++ai) _Pragma("unroll") for (int m = 0; m < 4; ++m) { const int row = u.pm * BM + ai * HALF + wr * 64 + m * 16 + fr; \
;         _Pragma("unroll") for (int bj = 0; bj < 2; ++bj) { const int cl = bj * HALF + wc * 32 + 8 * fq; f32x4 v0 = acc[ai][bj][m][0], v1 = acc[ai][bj][m][1]; __VA_ARGS__ } }
;     __device__ __forceinline__ void core(int row, int gc, f32x4 v0, f32x4 v1) const { *(u32x4*)(T + (size_t)row * 1024 + gc) = pack8(v0, v1); }
;     __device__ __forceinline__ void core(int row, int gc, f32x4 v0, f32x4 v1) const {
;         const size_t off = (size_t)row * 1024 + gc; f32x4 x0 = {0.f, 0.f, 0.f, 0.f}, x1 = {0.f, 0.f, 0.f, 0.f};
;         if (row < MROWS) { const float* b = row < MP ? xp + off : xs + (off - (size_t)MP * 1024); x0 = *(const f32x4*)b; x1 = *(const f32x4*)(b + 4); }
;         *(u32x4*)(Z + off) = pack8(x0 * ALPHA + v0, x1 * ALPHA + v1);
;     }
;     __device__ __forceinline__ void operator()(const f32x4 (&acc)[2][2][4][2], const Unit& u, int wr, int wc, int fr, int fq) const {
;         EPI_LOOP({ core(row, u.pn * BM + cl, v0, v1); })
.LBB0_993:
	s_or_b64 exec, exec, s[4:5]
	v_lshl_add_u64 v[46:47], v[48:49], 0, v[120:121]
	v_pk_add_f32 v[36:37], v[36:37], v[42:43]
	v_pk_add_f32 v[40:41], v[34:35], v[40:41]
	v_pk_add_f32 v[34:35], v[32:33], v[50:51]
	v_pk_add_f32 v[38:39], v[38:39], v[44:45]
	v_cvt_pk_bf16_f32 v32, v36, v37
	v_lshl_add_u64 v[36:37], v[46:47], 1, s[48:49]
	v_cvt_pk_bf16_f32 v33, v38, v39
	v_cvt_pk_bf16_f32 v34, v34, v35
	v_cvt_pk_bf16_f32 v35, v40, v41
	global_store_dwordx4 v[36:37], v[32:35], off
	v_mov_b32_e32 v42, 0
	v_mov_b32_e32 v43, 0
	v_add_u32_e32 v34, 0xa0, v146
	v_ashrrev_i32_e32 v35, 31, v34
	v_lshlrev_b64 v[32:33], 10, v[34:35]
	v_lshl_add_u64 v[40:41], v[32:33], 0, v[144:145]
	v_lshlrev_b64 v[38:39], 2, v[40:41]
	v_cmp_gt_i32_e64 s[44:45], s57, v34
	v_cmp_gt_i32_e32 vcc, s23, v34
	v_mov_b32_e32 v34, 0
	v_lshl_add_u64 v[36:37], s[8:9], 0, v[38:39]
	v_lshl_add_u64 v[38:39], s[46:47], 0, v[38:39]
	v_mov_b32_e32 v44, 0
	v_mov_b32_e32 v45, 0
	v_mov_b32_e32 v46, 0
	v_mov_b32_e32 v47, 0
	v_mov_b32_e32 v48, 0
	v_mov_b32_e32 v49, 0
	s_and_saveexec_b64 s[4:5], s[44:45]
	s_cbranch_execz .LBB0_995
	v_lshl_add_u64 v[42:43], v[38:39], 0, s[50:51]
	v_cndmask_b32_e32 v47, v43, v37, vcc
	v_cndmask_b32_e32 v46, v42, v36, vcc
	global_load_dwordx4 v[42:45], v[46:47], off
	global_load_dwordx4 v[50:53], v[46:47], off offset:16
	s_waitcnt vmcnt(0)
	v_pk_mul_f32 v[48:49], v[44:45], s[56:57] op_sel_hi:[1,0]
	v_pk_mul_f32 v[46:47], v[42:43], s[56:57] op_sel_hi:[1,0]
	v_pk_mul_f32 v[44:45], v[52:53], s[56:57] op_sel_hi:[1,0]
	v_pk_mul_f32 v[42:43], v[50:51], s[56:57] op_sel_hi:[1,0]
.LBB0_995:
	s_or_b64 exec, exec, s[4:5]
	v_pk_add_f32 v[28:29], v[28:29], v[46:47]
	v_pk_add_f32 v[44:45], v[26:27], v[44:45]
	v_pk_add_f32 v[26:27], v[24:25], v[42:43]
	v_pk_add_f32 v[30:31], v[30:31], v[48:49]
	v_cvt_pk_bf16_f32 v24, v28, v29
	v_lshl_add_u64 v[28:29], v[40:41], 1, s[48:49]
	v_cvt_pk_bf16_f32 v25, v30, v31
	v_cvt_pk_bf16_f32 v26, v26, v27
	v_cvt_pk_bf16_f32 v27, v44, v45
	global_store_dwordx4 v[28:29], v[24:27], off
	v_mov_b32_e32 v35, 0
	v_mov_b32_e32 v28, 0
	v_mov_b32_e32 v24, 0
	v_mov_b32_e32 v25, 0
	v_mov_b32_e32 v26, 0
	v_mov_b32_e32 v27, 0
	v_mov_b32_e32 v29, 0
	s_and_saveexec_b64 s[4:5], s[44:45]
	s_cbranch_execz .LBB0_997
	v_lshl_add_u64 v[24:25], v[36:37], 0, s[58:59]
	v_lshl_add_u64 v[26:27], v[38:39], 0, s[60:61]
	v_cndmask_b32_e32 v29, v27, v25, vcc
	v_cndmask_b32_e32 v28, v26, v24, vcc
	global_load_dwordx4 v[24:27], v[28:29], off
	global_load_dwordx4 v[34:37], v[28:29], off offset:16
	s_waitcnt vmcnt(0)
	v_pk_mul_f32 v[28:29], v[26:27], s[56:57] op_sel_hi:[1,0]
	v_pk_mul_f32 v[26:27], v[24:25], s[56:57] op_sel_hi:[1,0]
	v_pk_mul_f32 v[24:25], v[36:37], s[56:57] op_sel_hi:[1,0]
	v_pk_mul_f32 v[34:35], v[34:35], s[56:57] op_sel_hi:[1,0]
.LBB0_997:
	s_or_b64 exec, exec, s[4:5]
	v_lshl_add_u64 v[30:31], v[32:33], 0, v[120:121]
	v_pk_add_f32 v[20:21], v[20:21], v[26:27]
	v_pk_add_f32 v[24:25], v[18:19], v[24:25]
	v_pk_add_f32 v[18:19], v[16:17], v[34:35]
	v_pk_add_f32 v[22:23], v[22:23], v[28:29]
	v_cvt_pk_bf16_f32 v16, v20, v21
	v_lshl_add_u64 v[20:21], v[30:31], 1, s[48:49]
	v_cvt_pk_bf16_f32 v17, v22, v23
	v_cvt_pk_bf16_f32 v18, v18, v19
	v_cvt_pk_bf16_f32 v19, v24, v25
	global_store_dwordx4 v[20:21], v[16:19], off
	v_mov_b32_e32 v26, 0
	v_mov_b32_e32 v27, 0
	v_add_u32_e32 v18, 0xb0, v146
	v_ashrrev_i32_e32 v19, 31, v18
	v_lshlrev_b64 v[16:17], 10, v[18:19]
	v_lshl_add_u64 v[24:25], v[16:17], 0, v[144:145]
	v_lshlrev_b64 v[22:23], 2, v[24:25]
	v_cmp_gt_i32_e64 s[44:45], s57, v18
	v_cmp_gt_i32_e32 vcc, s23, v18
	v_mov_b32_e32 v18, 0
	v_lshl_add_u64 v[20:21], s[8:9], 0, v[22:23]
	v_lshl_add_u64 v[22:23], s[46:47], 0, v[22:23]
	v_mov_b32_e32 v28, 0
	v_mov_b32_e32 v29, 0
	v_mov_b32_e32 v30, 0
	v_mov_b32_e32 v31, 0
	v_mov_b32_e32 v32, 0
	v_mov_b32_e32 v33, 0
	s_and_saveexec_b64 s[4:5], s[44:45]
	s_cbranch_execz .LBB0_999
	v_lshl_add_u64 v[26:27], v[22:23], 0, s[50:51]
	v_cndmask_b32_e32 v31, v27, v21, vcc
	v_cndmask_b32_e32 v30, v26, v20, vcc
	global_load_dwordx4 v[26:29], v[30:31], off
	global_load_dwordx4 v[34:37], v[30:31], off offset:16
	s_waitcnt vmcnt(0)
	v_pk_mul_f32 v[32:33], v[28:29], s[56:57] op_sel_hi:[1,0]
	v_pk_mul_f32 v[30:31], v[26:27], s[56:57] op_sel_hi:[1,0]
	v_pk_mul_f32 v[28:29], v[36:37], s[56:57] op_sel_hi:[1,0]
	v_pk_mul_f32 v[26:27], v[34:35], s[56:57] op_sel_hi:[1,0]
.LBB0_999:
	s_or_b64 exec, exec, s[4:5]
	v_pk_add_f32 v[12:13], v[12:13], v[30:31]
	v_pk_add_f32 v[28:29], v[10:11], v[28:29]
	v_pk_add_f32 v[10:11], v[8:9], v[26:27]
	v_pk_add_f32 v[14:15], v[14:15], v[32:33]
	v_cvt_pk_bf16_f32 v8, v12, v13
	v_lshl_add_u64 v[12:13], v[24:25], 1, s[48:49]
	v_cvt_pk_bf16_f32 v9, v14, v15
	v_cvt_pk_bf16_f32 v10, v10, v11
	v_cvt_pk_bf16_f32 v11, v28, v29
	global_store_dwordx4 v[12:13], v[8:11], off
	v_mov_b32_e32 v19, 0
	v_mov_b32_e32 v12, 0
	v_mov_b32_e32 v8, 0
	v_mov_b32_e32 v9, 0
	v_mov_b32_e32 v10, 0
	v_mov_b32_e32 v11, 0
	v_mov_b32_e32 v13, 0
	s_and_saveexec_b64 s[4:5], s[44:45]
	s_cbranch_execz .LBB0_1001
	v_lshl_add_u64 v[8:9], v[20:21], 0, s[58:59]
	v_lshl_add_u64 v[10:11], v[22:23], 0, s[60:61]
	v_cndmask_b32_e32 v13, v11, v9, vcc
	v_cndmask_b32_e32 v12, v10, v8, vcc
	global_load_dwordx4 v[8:11], v[12:13], off
	global_load_dwordx4 v[18:21], v[12:13], off offset:16
	s_waitcnt vmcnt(0)
	v_pk_mul_f32 v[12:13], v[10:11], s[56:57] op_sel_hi:[1,0]
	v_pk_mul_f32 v[10:11], v[8:9], s[56:57] op_sel_hi:[1,0]
	v_pk_mul_f32 v[8:9], v[20:21], s[56:57] op_sel_hi:[1,0]
	v_pk_mul_f32 v[18:19], v[18:19], s[56:57] op_sel_hi:[1,0]
.LBB0_1001:
	s_or_b64 exec, exec, s[4:5]
	v_lshl_add_u64 v[14:15], v[16:17], 0, v[120:121]
	v_pk_add_f32 v[4:5], v[4:5], v[10:11]
	v_pk_add_f32 v[8:9], v[2:3], v[8:9]
	v_pk_add_f32 v[2:3], v[0:1], v[18:19]
	v_cvt_pk_bf16_f32 v0, v4, v5
	v_lshl_add_u64 v[4:5], v[14:15], 1, s[48:49]
	s_andn2_b64 vcc, exec, s[42:43]
	s_mov_b64 s[4:5], -1
	v_pk_add_f32 v[6:7], v[6:7], v[12:13]
	s_nop 0
	v_cvt_pk_bf16_f32 v1, v6, v7
	v_cvt_pk_bf16_f32 v2, v2, v3
	v_cvt_pk_bf16_f32 v3, v8, v9
	global_store_dwordx4 v[4:5], v[0:3], off
	s_cbranch_vccnz .LBB0_958
	s_and_b64 vcc, exec, s[40:41]
	s_cbranch_vccnz .LBB0_957
	s_barrier
	s_branch .LBB0_957
